# v18: v16 + in-proj epilogue row*ld as one 32-bit multiply (high word is zero) instead of the 64-bit v_mad_u64_u32 + 2 v_mul_lo_u32 + v_add3 sequence
# baseline (speedup 1.0000x reference)
; __device__ __forceinline__ unsigned pkbf(float lo, float hi) { f32x2v v = {lo, hi}; return __builtin_bit_cast(unsigned, __builtin_convertvector(v, bf2_t)); }
;     __device__ __forceinline__ void operator()(const pg8::f32x4 (&acc)[2][2][4][2], const pg8::Unit& u, int wr, int wc, int fr, int fq) const {
;     ...
;         float rstd[2][4];
; #pragma unroll
;         for (int ai = 0; ai < 2; ++ai)
; #pragma unroll
;             for (int m = 0; m < 4; ++m) rstd[ai][m] = rowsq[u.pm * 256 + ai * 128 + wr * 64 + m * 16 + fr];
; #pragma unroll
;         for (int ai = 0; ai < 2; ++ai)
; #pragma unroll
;             for (int m = 0; m < 4; ++m) rstd[ai][m] = __builtin_amdgcn_rsqf(rstd[ai][m] * (1.0f / 1024.0f) + EPS);
;     template <int TYPE  >
;     __device__ __forceinline__ void rows(const pg8::f32x4 (&acc)[2][2][4][2], const pg8::Unit& u, int wr, int fr, int fq, const float (&rstd)[2][4], bf16_t* dst, int ld, const float* gain, float qs) const {
;     ...
; #pragma unroll
;                     for (int bj = 0; bj < 2; ++bj)
; #pragma unroll
;                         for (int n = 0; n < 2; ++n)
; #pragma unroll
;                             for (int e = 0; e < 4; ++e) { const float z = acc[ai][bj][m][n][e] * rstd[ai][m]; v[bj][n][e] = TYPE == 3 ? z * __builtin_amdgcn_rcpf(1.0f + __expf(-z)) : z; }
;                 }
;                 bf16_t* rowp = dst + (size_t)row * ld;
; #pragma unroll
;                 for (int bj = 0; bj < 2; ++bj) {
;                     u32x4 w; w.x = pkbf(v[bj][0][0], v[bj][0][1]); w.y = pkbf(v[bj][0][2], v[bj][0][3]); w.z = pkbf(v[bj][1][0], v[bj][1][1]); w.w = pkbf(v[bj][1][2], v[bj][1][3]);
;                     *(u32x4*)(rowp + 32 * bj) = w;
;                 }
.LBB0_329:
	s_lshl_b32 s19, s34, 8
	v_add_u32_e32 v192, s19, v163
	v_ashrrev_i32_e32 v193, 31, v192
	v_lshl_add_u64 v[130:131], v[192:193], 2, s[14:15]
	global_load_dword v112, v[130:131], off
	global_load_dword v132, v[130:131], off offset:64
	global_load_dword v133, v[130:131], off offset:128
	global_load_dword v134, v[130:131], off offset:192
	global_load_dword v135, v[130:131], off offset:512
	global_load_dword v136, v[130:131], off offset:576
	global_load_dword v137, v[130:131], off offset:640
	s_nop 0
	global_load_dword v131, v[130:131], off offset:704
	v_add_u32_e32 v130, s64, v162
	s_mov_b64 s[34:35], -1
	s_andn2_b64 vcc, exec, s[46:47]
	s_waitcnt vmcnt(0)
	v_fmamk_f32 v112, v112, 0x3a800000, v198
	v_fmamk_f32 v132, v132, 0x3a800000, v198
	v_fmamk_f32 v133, v133, 0x3a800000, v198
	v_fmamk_f32 v134, v134, 0x3a800000, v198
	v_fmamk_f32 v135, v135, 0x3a800000, v198
	v_fmamk_f32 v136, v136, 0x3a800000, v198
	v_fmamk_f32 v137, v137, 0x3a800000, v198
	v_fmamk_f32 v131, v131, 0x3a800000, v198
	v_rsq_f32_e32 v190, v112
	v_rsq_f32_e32 v184, v132
	v_rsq_f32_e32 v182, v133
	v_rsq_f32_e32 v180, v134
	v_rsq_f32_e32 v178, v135
	v_rsq_f32_e32 v176, v136
	v_rsq_f32_e32 v174, v137
	v_rsq_f32_e32 v172, v131
	v_ashrrev_i32_e32 v131, 31, v130
	v_lshl_add_u64 v[170:171], v[130:131], 1, s[44:45]
	s_cbranch_vccz .LBB0_335
	s_xor_b64 s[42:43], s[42:43], -1
	v_mul_f32_e32 v130, v118, v190
	s_and_b64 vcc, exec, s[42:43]
	v_mul_f32_e32 v131, v119, v190
	s_cbranch_vccz .LBB0_332
	v_mul_f32_e32 v112, 0xbfb8aa3b, v130
	v_exp_f32_e32 v112, v112
	v_pk_mul_f32 v[134:135], v[120:121], v[190:191] op_sel_hi:[1,0]
	s_nop 0
	v_add_f32_e32 v112, 1.0, v112
	v_rcp_f32_e32 v132, v112
	v_mul_f32_e32 v112, 0xbfb8aa3b, v131
	v_exp_f32_e32 v112, v112
	s_nop 0
	v_add_f32_e32 v112, 1.0, v112
	v_rcp_f32_e32 v133, v112
	v_mul_f32_e32 v112, 0xbfb8aa3b, v134
	v_exp_f32_e32 v112, v112
	v_pk_mul_f32 v[132:133], v[130:131], v[132:133]
	s_nop 0
	v_cvt_pk_bf16_f32 v132, v132, v133
	v_add_f32_e32 v112, 1.0, v112
	v_rcp_f32_e32 v136, v112
	v_mul_f32_e32 v112, 0xbfb8aa3b, v135
	v_exp_f32_e32 v112, v112
	s_nop 0
	v_add_f32_e32 v112, 1.0, v112
	v_rcp_f32_e32 v137, v112
	s_nop 0
	v_pk_mul_f32 v[134:135], v[134:135], v[136:137]
	v_pk_mul_f32 v[136:137], v[114:115], v[190:191] op_sel_hi:[1,0]
	v_cvt_pk_bf16_f32 v133, v134, v135
	v_mul_f32_e32 v112, 0xbfb8aa3b, v136
	v_exp_f32_e32 v112, v112
	s_nop 0
	v_add_f32_e32 v112, 1.0, v112
	v_rcp_f32_e32 v138, v112
	v_mul_f32_e32 v112, 0xbfb8aa3b, v137
	v_exp_f32_e32 v112, v112
	s_nop 0
	v_add_f32_e32 v112, 1.0, v112
	v_rcp_f32_e32 v139, v112
	s_nop 0
	v_pk_mul_f32 v[136:137], v[136:137], v[138:139]
	v_pk_mul_f32 v[138:139], v[116:117], v[190:191] op_sel_hi:[1,0]
	v_cvt_pk_bf16_f32 v134, v136, v137
	v_mul_f32_e32 v112, 0xbfb8aa3b, v138
	v_exp_f32_e32 v112, v112
	s_nop 0
	v_add_f32_e32 v112, 1.0, v112
	v_rcp_f32_e32 v140, v112
	v_mul_f32_e32 v112, 0xbfb8aa3b, v139
	v_exp_f32_e32 v112, v112
	s_nop 0
	v_add_f32_e32 v112, 1.0, v112
	v_rcp_f32_e32 v141, v112
	s_nop 0
	v_pk_mul_f32 v[138:139], v[138:139], v[140:141]
	v_pk_mul_f32 v[140:141], v[126:127], v[190:191] op_sel_hi:[1,0]
	v_cvt_pk_bf16_f32 v135, v138, v139
	v_mul_f32_e32 v112, 0xbfb8aa3b, v140
	v_exp_f32_e32 v112, v112
	s_nop 0
	v_add_f32_e32 v112, 1.0, v112
	v_rcp_f32_e32 v142, v112
	v_mul_f32_e32 v112, 0xbfb8aa3b, v141
	v_exp_f32_e32 v112, v112
	s_nop 0
	v_add_f32_e32 v112, 1.0, v112
	v_rcp_f32_e32 v143, v112
	s_nop 0
	v_pk_mul_f32 v[140:141], v[140:141], v[142:143]
	v_pk_mul_f32 v[142:143], v[128:129], v[190:191] op_sel_hi:[1,0]
	s_nop 0
	v_mul_f32_e32 v112, 0xbfb8aa3b, v142
	v_exp_f32_e32 v112, v112
	s_nop 0
	v_add_f32_e32 v112, 1.0, v112
	v_rcp_f32_e32 v144, v112
	v_mul_f32_e32 v112, 0xbfb8aa3b, v143
	v_exp_f32_e32 v112, v112
	s_nop 0
	v_add_f32_e32 v112, 1.0, v112
	v_rcp_f32_e32 v145, v112
	s_nop 0
	v_pk_mul_f32 v[142:143], v[142:143], v[144:145]
	v_pk_mul_f32 v[144:145], v[122:123], v[190:191] op_sel_hi:[1,0]
	s_nop 0
	v_mul_f32_e32 v112, 0xbfb8aa3b, v144
	v_exp_f32_e32 v112, v112
	s_nop 0
	v_add_f32_e32 v112, 1.0, v112
	v_rcp_f32_e32 v146, v112
	v_mul_f32_e32 v112, 0xbfb8aa3b, v145
	v_exp_f32_e32 v112, v112
	s_nop 0
	v_add_f32_e32 v112, 1.0, v112
	v_rcp_f32_e32 v147, v112
	s_nop 0
	v_pk_mul_f32 v[144:145], v[144:145], v[146:147]
	v_pk_mul_f32 v[146:147], v[124:125], v[190:191] op_sel_hi:[1,0]
	s_nop 0
	v_mul_f32_e32 v112, 0xbfb8aa3b, v146
	v_exp_f32_e32 v112, v112
	s_nop 0
	v_add_f32_e32 v112, 1.0, v112
	v_rcp_f32_e32 v148, v112
	v_mul_f32_e32 v112, 0xbfb8aa3b, v147
	v_exp_f32_e32 v112, v112
	s_nop 0
	v_add_f32_e32 v112, 1.0, v112
	v_rcp_f32_e32 v149, v112
	s_nop 0
	v_pk_mul_f32 v[146:147], v[146:147], v[148:149]
	v_mul_lo_u32 v148, s26, v192
	v_mov_b32_e64 v149, 0
	v_lshl_add_u64 v[148:149], v[148:149], 1, v[170:171]
	global_store_dwordx4 v[148:149], v[132:135], off
	s_nop 1
	v_cvt_pk_bf16_f32 v132, v140, v141
	v_cvt_pk_bf16_f32 v133, v142, v143
	v_cvt_pk_bf16_f32 v134, v144, v145
	v_cvt_pk_bf16_f32 v135, v146, v147
	global_store_dwordx4 v[148:149], v[132:135], off offset:64
	s_nop 1
	v_pk_mul_f32 v[132:133], v[104:105], v[184:185] op_sel_hi:[1,0]
	s_nop 0
	v_mul_f32_e32 v112, 0xbfb8aa3b, v132
	v_exp_f32_e32 v112, v112
	s_nop 0
	v_add_f32_e32 v112, 1.0, v112
	v_rcp_f32_e32 v134, v112
	v_mul_f32_e32 v112, 0xbfb8aa3b, v133
	v_exp_f32_e32 v112, v112
	s_nop 0
	v_add_f32_e32 v112, 1.0, v112
	v_rcp_f32_e32 v135, v112
	s_nop 0
	v_pk_mul_f32 v[132:133], v[132:133], v[134:135]
	v_pk_mul_f32 v[134:135], v[106:107], v[184:185] op_sel_hi:[1,0]
	v_cvt_pk_bf16_f32 v132, v132, v133
	v_mul_f32_e32 v112, 0xbfb8aa3b, v134
	v_exp_f32_e32 v112, v112
	s_nop 0
	v_add_f32_e32 v112, 1.0, v112
	v_rcp_f32_e32 v136, v112
; __device__ __forceinline__ unsigned pkbf(float lo, float hi) { f32x2v v = {lo, hi}; return __builtin_bit_cast(unsigned, __builtin_convertvector(v, bf2_t)); }
;     template <int TYPE  >
;     __device__ __forceinline__ void rows(const pg8::f32x4 (&acc)[2][2][4][2], const pg8::Unit& u, int wr, int fr, int fq, const float (&rstd)[2][4], bf16_t* dst, int ld, const float* gain, float qs) const {
;     ...
; #pragma unroll
;                     for (int bj = 0; bj < 2; ++bj)
; #pragma unroll
;                         for (int n = 0; n < 2; ++n)
; #pragma unroll
;                             for (int e = 0; e < 4; ++e) { const float z = acc[ai][bj][m][n][e] * rstd[ai][m]; v[bj][n][e] = TYPE == 3 ? z * __builtin_amdgcn_rcpf(1.0f + __expf(-z)) : z; }
;                 }
;                 bf16_t* rowp = dst + (size_t)row * ld;
; #pragma unroll
;                 for (int bj = 0; bj < 2; ++bj) {
;                     u32x4 w; w.x = pkbf(v[bj][0][0], v[bj][0][1]); w.y = pkbf(v[bj][0][2], v[bj][0][3]); w.z = pkbf(v[bj][1][0], v[bj][1][1]); w.w = pkbf(v[bj][1][2], v[bj][1][3]);
;                     *(u32x4*)(rowp + 32 * bj) = w;
;                 }
	v_mul_f32_e32 v112, 0xbfb8aa3b, v135
	v_exp_f32_e32 v112, v112
	s_nop 0
	v_add_f32_e32 v112, 1.0, v112
	v_rcp_f32_e32 v137, v112
	s_nop 0
	v_pk_mul_f32 v[134:135], v[134:135], v[136:137]
	v_pk_mul_f32 v[136:137], v[96:97], v[184:185] op_sel_hi:[1,0]
	v_cvt_pk_bf16_f32 v133, v134, v135
	v_mul_f32_e32 v112, 0xbfb8aa3b, v136
	v_exp_f32_e32 v112, v112
	s_nop 0
	v_add_f32_e32 v112, 1.0, v112
	v_rcp_f32_e32 v138, v112
	v_mul_f32_e32 v112, 0xbfb8aa3b, v137
	v_exp_f32_e32 v112, v112
	s_nop 0
	v_add_f32_e32 v112, 1.0, v112
	v_rcp_f32_e32 v139, v112
	s_nop 0
	v_pk_mul_f32 v[136:137], v[136:137], v[138:139]
	v_pk_mul_f32 v[138:139], v[98:99], v[184:185] op_sel_hi:[1,0]
	v_cvt_pk_bf16_f32 v134, v136, v137
	v_mul_f32_e32 v112, 0xbfb8aa3b, v138
	v_exp_f32_e32 v112, v112
	s_nop 0
	v_add_f32_e32 v112, 1.0, v112
	v_rcp_f32_e32 v140, v112
	v_mul_f32_e32 v112, 0xbfb8aa3b, v139
	v_exp_f32_e32 v112, v112
	s_nop 0
	v_add_f32_e32 v112, 1.0, v112
	v_rcp_f32_e32 v141, v112
	s_nop 0
	v_pk_mul_f32 v[138:139], v[138:139], v[140:141]
	v_pk_mul_f32 v[140:141], v[108:109], v[184:185] op_sel_hi:[1,0]
	v_cvt_pk_bf16_f32 v135, v138, v139
	v_mul_f32_e32 v112, 0xbfb8aa3b, v140
	v_exp_f32_e32 v112, v112
	s_nop 0
	v_add_f32_e32 v112, 1.0, v112
	v_rcp_f32_e32 v142, v112
	v_mul_f32_e32 v112, 0xbfb8aa3b, v141
	v_exp_f32_e32 v112, v112
	s_nop 0
	v_add_f32_e32 v112, 1.0, v112
	v_rcp_f32_e32 v143, v112
	s_nop 0
	v_pk_mul_f32 v[140:141], v[140:141], v[142:143]
	v_pk_mul_f32 v[142:143], v[110:111], v[184:185] op_sel_hi:[1,0]
	s_nop 0
	v_mul_f32_e32 v112, 0xbfb8aa3b, v142
	v_exp_f32_e32 v112, v112
	s_nop 0
	v_add_f32_e32 v112, 1.0, v112
	v_rcp_f32_e32 v144, v112
	v_mul_f32_e32 v112, 0xbfb8aa3b, v143
	v_exp_f32_e32 v112, v112
	s_nop 0
	v_add_f32_e32 v112, 1.0, v112
	v_rcp_f32_e32 v145, v112
	s_nop 0
	v_pk_mul_f32 v[142:143], v[142:143], v[144:145]
	v_pk_mul_f32 v[144:145], v[100:101], v[184:185] op_sel_hi:[1,0]
	s_nop 0
	v_mul_f32_e32 v112, 0xbfb8aa3b, v144
	v_exp_f32_e32 v112, v112
	s_nop 0
	v_add_f32_e32 v112, 1.0, v112
	v_rcp_f32_e32 v146, v112
	v_mul_f32_e32 v112, 0xbfb8aa3b, v145
	v_exp_f32_e32 v112, v112
	s_nop 0
	v_add_f32_e32 v112, 1.0, v112
	v_rcp_f32_e32 v147, v112
	s_nop 0
	v_pk_mul_f32 v[144:145], v[144:145], v[146:147]
	v_pk_mul_f32 v[146:147], v[102:103], v[184:185] op_sel_hi:[1,0]
	s_nop 0
	v_mul_f32_e32 v112, 0xbfb8aa3b, v146
	v_exp_f32_e32 v112, v112
	s_nop 0
	v_add_f32_e32 v112, 1.0, v112
	v_rcp_f32_e32 v148, v112
	v_mul_f32_e32 v112, 0xbfb8aa3b, v147
	v_exp_f32_e32 v112, v112
	s_nop 0
	v_add_f32_e32 v112, 1.0, v112
	v_rcp_f32_e32 v149, v112
	v_add_u32_e32 v112, s19, v175
	s_nop 0
	v_pk_mul_f32 v[146:147], v[146:147], v[148:149]
	v_ashrrev_i32_e32 v148, 31, v112
	s_nop 0
	v_mul_lo_u32 v148, s26, v112
	v_mov_b32_e64 v149, 0
	v_lshl_add_u64 v[148:149], v[148:149], 1, v[170:171]
	global_store_dwordx4 v[148:149], v[132:135], off
	s_nop 1
	v_cvt_pk_bf16_f32 v132, v140, v141
	v_cvt_pk_bf16_f32 v133, v142, v143
	v_cvt_pk_bf16_f32 v134, v144, v145
	v_cvt_pk_bf16_f32 v135, v146, v147
	global_store_dwordx4 v[148:149], v[132:135], off offset:64
	s_nop 1
	v_pk_mul_f32 v[132:133], v[88:89], v[182:183] op_sel_hi:[1,0]
	s_nop 0
	v_mul_f32_e32 v112, 0xbfb8aa3b, v132
	v_exp_f32_e32 v112, v112
	s_nop 0
	v_add_f32_e32 v112, 1.0, v112
	v_rcp_f32_e32 v134, v112
	v_mul_f32_e32 v112, 0xbfb8aa3b, v133
	v_exp_f32_e32 v112, v112
	s_nop 0
	v_add_f32_e32 v112, 1.0, v112
	v_rcp_f32_e32 v135, v112
	s_nop 0
	v_pk_mul_f32 v[132:133], v[132:133], v[134:135]
	v_pk_mul_f32 v[134:135], v[90:91], v[182:183] op_sel_hi:[1,0]
	v_cvt_pk_bf16_f32 v132, v132, v133
	v_mul_f32_e32 v112, 0xbfb8aa3b, v134
	v_exp_f32_e32 v112, v112
	s_nop 0
	v_add_f32_e32 v112, 1.0, v112
	v_rcp_f32_e32 v136, v112
	v_mul_f32_e32 v112, 0xbfb8aa3b, v135
	v_exp_f32_e32 v112, v112
	s_nop 0
	v_add_f32_e32 v112, 1.0, v112
	v_rcp_f32_e32 v137, v112
	s_nop 0
	v_pk_mul_f32 v[134:135], v[134:135], v[136:137]
	v_pk_mul_f32 v[136:137], v[80:81], v[182:183] op_sel_hi:[1,0]
	v_cvt_pk_bf16_f32 v133, v134, v135
	v_mul_f32_e32 v112, 0xbfb8aa3b, v136
	v_exp_f32_e32 v112, v112
	s_nop 0
	v_add_f32_e32 v112, 1.0, v112
	v_rcp_f32_e32 v138, v112
	v_mul_f32_e32 v112, 0xbfb8aa3b, v137
	v_exp_f32_e32 v112, v112
	s_nop 0
	v_add_f32_e32 v112, 1.0, v112
	v_rcp_f32_e32 v139, v112
	s_nop 0
	v_pk_mul_f32 v[136:137], v[136:137], v[138:139]
	v_pk_mul_f32 v[138:139], v[82:83], v[182:183] op_sel_hi:[1,0]
	v_cvt_pk_bf16_f32 v134, v136, v137
	v_mul_f32_e32 v112, 0xbfb8aa3b, v138
	v_exp_f32_e32 v112, v112
	s_nop 0
	v_add_f32_e32 v112, 1.0, v112
	v_rcp_f32_e32 v140, v112
	v_mul_f32_e32 v112, 0xbfb8aa3b, v139
	v_exp_f32_e32 v112, v112
	s_nop 0
	v_add_f32_e32 v112, 1.0, v112
	v_rcp_f32_e32 v141, v112
	s_nop 0
	v_pk_mul_f32 v[138:139], v[138:139], v[140:141]
	v_pk_mul_f32 v[140:141], v[92:93], v[182:183] op_sel_hi:[1,0]
	v_cvt_pk_bf16_f32 v135, v138, v139
	v_mul_f32_e32 v112, 0xbfb8aa3b, v140
	v_exp_f32_e32 v112, v112
	s_nop 0
	v_add_f32_e32 v112, 1.0, v112
	v_rcp_f32_e32 v142, v112
	v_mul_f32_e32 v112, 0xbfb8aa3b, v141
	v_exp_f32_e32 v112, v112
	s_nop 0
	v_add_f32_e32 v112, 1.0, v112
	v_rcp_f32_e32 v143, v112
	s_nop 0
	v_pk_mul_f32 v[140:141], v[140:141], v[142:143]
	v_pk_mul_f32 v[142:143], v[94:95], v[182:183] op_sel_hi:[1,0]
	s_nop 0
	v_mul_f32_e32 v112, 0xbfb8aa3b, v142
	v_exp_f32_e32 v112, v112
	s_nop 0
	v_add_f32_e32 v112, 1.0, v112
	v_rcp_f32_e32 v144, v112
	v_mul_f32_e32 v112, 0xbfb8aa3b, v143
	v_exp_f32_e32 v112, v112
	s_nop 0
	v_add_f32_e32 v112, 1.0, v112
	v_rcp_f32_e32 v145, v112
	s_nop 0
	v_pk_mul_f32 v[142:143], v[142:143], v[144:145]
	v_pk_mul_f32 v[144:145], v[84:85], v[182:183] op_sel_hi:[1,0]
	s_nop 0
	v_mul_f32_e32 v112, 0xbfb8aa3b, v144
; __device__ __forceinline__ unsigned pkbf(float lo, float hi) { f32x2v v = {lo, hi}; return __builtin_bit_cast(unsigned, __builtin_convertvector(v, bf2_t)); }
;     template <int TYPE  >
;     __device__ __forceinline__ void rows(const pg8::f32x4 (&acc)[2][2][4][2], const pg8::Unit& u, int wr, int fr, int fq, const float (&rstd)[2][4], bf16_t* dst, int ld, const float* gain, float qs) const {
;     ...
; #pragma unroll
;                     for (int bj = 0; bj < 2; ++bj)
; #pragma unroll
;                         for (int n = 0; n < 2; ++n)
; #pragma unroll
;                             for (int e = 0; e < 4; ++e) { const float z = acc[ai][bj][m][n][e] * rstd[ai][m]; v[bj][n][e] = TYPE == 3 ? z * __builtin_amdgcn_rcpf(1.0f + __expf(-z)) : z; }
;                 }
;                 bf16_t* rowp = dst + (size_t)row * ld;
; #pragma unroll
;                 for (int bj = 0; bj < 2; ++bj) {
;                     u32x4 w; w.x = pkbf(v[bj][0][0], v[bj][0][1]); w.y = pkbf(v[bj][0][2], v[bj][0][3]); w.z = pkbf(v[bj][1][0], v[bj][1][1]); w.w = pkbf(v[bj][1][2], v[bj][1][3]);
;                     *(u32x4*)(rowp + 32 * bj) = w;
;                 }
	v_exp_f32_e32 v112, v112
	s_nop 0
	v_add_f32_e32 v112, 1.0, v112
	v_rcp_f32_e32 v146, v112
	v_mul_f32_e32 v112, 0xbfb8aa3b, v145
	v_exp_f32_e32 v112, v112
	s_nop 0
	v_add_f32_e32 v112, 1.0, v112
	v_rcp_f32_e32 v147, v112
	s_nop 0
	v_pk_mul_f32 v[144:145], v[144:145], v[146:147]
	v_pk_mul_f32 v[146:147], v[86:87], v[182:183] op_sel_hi:[1,0]
	s_nop 0
	v_mul_f32_e32 v112, 0xbfb8aa3b, v146
	v_exp_f32_e32 v112, v112
	s_nop 0
	v_add_f32_e32 v112, 1.0, v112
	v_rcp_f32_e32 v148, v112
	v_mul_f32_e32 v112, 0xbfb8aa3b, v147
	v_exp_f32_e32 v112, v112
	s_nop 0
	v_add_f32_e32 v112, 1.0, v112
	v_rcp_f32_e32 v149, v112
	v_add_u32_e32 v112, s19, v177
	s_nop 0
	v_pk_mul_f32 v[146:147], v[146:147], v[148:149]
	v_ashrrev_i32_e32 v148, 31, v112
	s_nop 0
	v_mul_lo_u32 v148, s26, v112
	v_mov_b32_e64 v149, 0
	v_lshl_add_u64 v[148:149], v[148:149], 1, v[170:171]
	global_store_dwordx4 v[148:149], v[132:135], off
	s_nop 1
	v_cvt_pk_bf16_f32 v132, v140, v141
	v_cvt_pk_bf16_f32 v133, v142, v143
	v_cvt_pk_bf16_f32 v134, v144, v145
	v_cvt_pk_bf16_f32 v135, v146, v147
	global_store_dwordx4 v[148:149], v[132:135], off offset:64
	s_nop 1
	v_pk_mul_f32 v[132:133], v[72:73], v[180:181] op_sel_hi:[1,0]
	s_nop 0
	v_mul_f32_e32 v112, 0xbfb8aa3b, v132
	v_exp_f32_e32 v112, v112
	s_nop 0
	v_add_f32_e32 v112, 1.0, v112
	v_rcp_f32_e32 v134, v112
	v_mul_f32_e32 v112, 0xbfb8aa3b, v133
	v_exp_f32_e32 v112, v112
	s_nop 0
	v_add_f32_e32 v112, 1.0, v112
	v_rcp_f32_e32 v135, v112
	s_nop 0
	v_pk_mul_f32 v[132:133], v[132:133], v[134:135]
	v_pk_mul_f32 v[134:135], v[74:75], v[180:181] op_sel_hi:[1,0]
	v_cvt_pk_bf16_f32 v132, v132, v133
	v_mul_f32_e32 v112, 0xbfb8aa3b, v134
	v_exp_f32_e32 v112, v112
	s_nop 0
	v_add_f32_e32 v112, 1.0, v112
	v_rcp_f32_e32 v136, v112
	v_mul_f32_e32 v112, 0xbfb8aa3b, v135
	v_exp_f32_e32 v112, v112
	s_nop 0
	v_add_f32_e32 v112, 1.0, v112
	v_rcp_f32_e32 v137, v112
	s_nop 0
	v_pk_mul_f32 v[134:135], v[134:135], v[136:137]
	v_pk_mul_f32 v[136:137], v[64:65], v[180:181] op_sel_hi:[1,0]
	v_cvt_pk_bf16_f32 v133, v134, v135
	v_mul_f32_e32 v112, 0xbfb8aa3b, v136
	v_exp_f32_e32 v112, v112
	s_nop 0
	v_add_f32_e32 v112, 1.0, v112
	v_rcp_f32_e32 v138, v112
	v_mul_f32_e32 v112, 0xbfb8aa3b, v137
	v_exp_f32_e32 v112, v112
	s_nop 0
	v_add_f32_e32 v112, 1.0, v112
	v_rcp_f32_e32 v139, v112
	s_nop 0
	v_pk_mul_f32 v[136:137], v[136:137], v[138:139]
	v_pk_mul_f32 v[138:139], v[66:67], v[180:181] op_sel_hi:[1,0]
	v_cvt_pk_bf16_f32 v134, v136, v137
	v_mul_f32_e32 v112, 0xbfb8aa3b, v138
	v_exp_f32_e32 v112, v112
	s_nop 0
	v_add_f32_e32 v112, 1.0, v112
	v_rcp_f32_e32 v140, v112
	v_mul_f32_e32 v112, 0xbfb8aa3b, v139
	v_exp_f32_e32 v112, v112
	s_nop 0
	v_add_f32_e32 v112, 1.0, v112
	v_rcp_f32_e32 v141, v112
	s_nop 0
	v_pk_mul_f32 v[138:139], v[138:139], v[140:141]
	v_pk_mul_f32 v[140:141], v[76:77], v[180:181] op_sel_hi:[1,0]
	v_cvt_pk_bf16_f32 v135, v138, v139
	v_mul_f32_e32 v112, 0xbfb8aa3b, v140
	v_exp_f32_e32 v112, v112
	s_nop 0
	v_add_f32_e32 v112, 1.0, v112
	v_rcp_f32_e32 v142, v112
	v_mul_f32_e32 v112, 0xbfb8aa3b, v141
	v_exp_f32_e32 v112, v112
	s_nop 0
	v_add_f32_e32 v112, 1.0, v112
	v_rcp_f32_e32 v143, v112
	s_nop 0
	v_pk_mul_f32 v[140:141], v[140:141], v[142:143]
	v_pk_mul_f32 v[142:143], v[78:79], v[180:181] op_sel_hi:[1,0]
	s_nop 0
	v_mul_f32_e32 v112, 0xbfb8aa3b, v142
	v_exp_f32_e32 v112, v112
	s_nop 0
	v_add_f32_e32 v112, 1.0, v112
	v_rcp_f32_e32 v144, v112
	v_mul_f32_e32 v112, 0xbfb8aa3b, v143
	v_exp_f32_e32 v112, v112
	s_nop 0
	v_add_f32_e32 v112, 1.0, v112
	v_rcp_f32_e32 v145, v112
	s_nop 0
	v_pk_mul_f32 v[142:143], v[142:143], v[144:145]
	v_pk_mul_f32 v[144:145], v[68:69], v[180:181] op_sel_hi:[1,0]
	s_nop 0
	v_mul_f32_e32 v112, 0xbfb8aa3b, v144
	v_exp_f32_e32 v112, v112
	s_nop 0
	v_add_f32_e32 v112, 1.0, v112
	v_rcp_f32_e32 v146, v112
	v_mul_f32_e32 v112, 0xbfb8aa3b, v145
	v_exp_f32_e32 v112, v112
	s_nop 0
	v_add_f32_e32 v112, 1.0, v112
	v_rcp_f32_e32 v147, v112
	s_nop 0
	v_pk_mul_f32 v[144:145], v[144:145], v[146:147]
	v_pk_mul_f32 v[146:147], v[70:71], v[180:181] op_sel_hi:[1,0]
	s_nop 0
	v_mul_f32_e32 v112, 0xbfb8aa3b, v146
	v_exp_f32_e32 v112, v112
	s_nop 0
	v_add_f32_e32 v112, 1.0, v112
	v_rcp_f32_e32 v148, v112
	v_mul_f32_e32 v112, 0xbfb8aa3b, v147
	v_exp_f32_e32 v112, v112
	s_nop 0
	v_add_f32_e32 v112, 1.0, v112
	v_rcp_f32_e32 v149, v112
	v_add_u32_e32 v112, s19, v179
	s_nop 0
	v_pk_mul_f32 v[146:147], v[146:147], v[148:149]
	v_ashrrev_i32_e32 v148, 31, v112
	s_nop 0
	v_mul_lo_u32 v148, s26, v112
	v_mov_b32_e64 v149, 0
	v_lshl_add_u64 v[148:149], v[148:149], 1, v[170:171]
	global_store_dwordx4 v[148:149], v[132:135], off
	s_nop 1
	v_cvt_pk_bf16_f32 v132, v140, v141
	v_cvt_pk_bf16_f32 v133, v142, v143
	v_cvt_pk_bf16_f32 v134, v144, v145
	v_cvt_pk_bf16_f32 v135, v146, v147
	global_store_dwordx4 v[148:149], v[132:135], off offset:64
	s_nop 1
	v_pk_mul_f32 v[132:133], v[56:57], v[178:179] op_sel_hi:[1,0]
	s_nop 0
	v_mul_f32_e32 v112, 0xbfb8aa3b, v132
	v_exp_f32_e32 v112, v112
	s_nop 0
	v_add_f32_e32 v112, 1.0, v112
	v_rcp_f32_e32 v134, v112
	v_mul_f32_e32 v112, 0xbfb8aa3b, v133
	v_exp_f32_e32 v112, v112
	s_nop 0
	v_add_f32_e32 v112, 1.0, v112
	v_rcp_f32_e32 v135, v112
	s_nop 0
	v_pk_mul_f32 v[132:133], v[132:133], v[134:135]
	v_pk_mul_f32 v[134:135], v[58:59], v[178:179] op_sel_hi:[1,0]
	v_cvt_pk_bf16_f32 v132, v132, v133
	v_mul_f32_e32 v112, 0xbfb8aa3b, v134
	v_exp_f32_e32 v112, v112
	s_nop 0
	v_add_f32_e32 v112, 1.0, v112
	v_rcp_f32_e32 v136, v112
	v_mul_f32_e32 v112, 0xbfb8aa3b, v135
	v_exp_f32_e32 v112, v112
	s_nop 0
	v_add_f32_e32 v112, 1.0, v112
	v_rcp_f32_e32 v137, v112
	s_nop 0
	v_pk_mul_f32 v[134:135], v[134:135], v[136:137]
; __device__ __forceinline__ unsigned pkbf(float lo, float hi) { f32x2v v = {lo, hi}; return __builtin_bit_cast(unsigned, __builtin_convertvector(v, bf2_t)); }
;     template <int TYPE  >
;     __device__ __forceinline__ void rows(const pg8::f32x4 (&acc)[2][2][4][2], const pg8::Unit& u, int wr, int fr, int fq, const float (&rstd)[2][4], bf16_t* dst, int ld, const float* gain, float qs) const {
;     ...
; #pragma unroll
;                     for (int bj = 0; bj < 2; ++bj)
; #pragma unroll
;                         for (int n = 0; n < 2; ++n)
; #pragma unroll
;                             for (int e = 0; e < 4; ++e) { const float z = acc[ai][bj][m][n][e] * rstd[ai][m]; v[bj][n][e] = TYPE == 3 ? z * __builtin_amdgcn_rcpf(1.0f + __expf(-z)) : z; }
;                 }
;                 bf16_t* rowp = dst + (size_t)row * ld;
; #pragma unroll
;                 for (int bj = 0; bj < 2; ++bj) {
;                     u32x4 w; w.x = pkbf(v[bj][0][0], v[bj][0][1]); w.y = pkbf(v[bj][0][2], v[bj][0][3]); w.z = pkbf(v[bj][1][0], v[bj][1][1]); w.w = pkbf(v[bj][1][2], v[bj][1][3]);
;                     *(u32x4*)(rowp + 32 * bj) = w;
;                 }
	v_pk_mul_f32 v[136:137], v[48:49], v[178:179] op_sel_hi:[1,0]
	v_cvt_pk_bf16_f32 v133, v134, v135
	v_mul_f32_e32 v112, 0xbfb8aa3b, v136
	v_exp_f32_e32 v112, v112
	s_nop 0
	v_add_f32_e32 v112, 1.0, v112
	v_rcp_f32_e32 v138, v112
	v_mul_f32_e32 v112, 0xbfb8aa3b, v137
	v_exp_f32_e32 v112, v112
	s_nop 0
	v_add_f32_e32 v112, 1.0, v112
	v_rcp_f32_e32 v139, v112
	s_nop 0
	v_pk_mul_f32 v[136:137], v[136:137], v[138:139]
	v_pk_mul_f32 v[138:139], v[50:51], v[178:179] op_sel_hi:[1,0]
	v_cvt_pk_bf16_f32 v134, v136, v137
	v_mul_f32_e32 v112, 0xbfb8aa3b, v138
	v_exp_f32_e32 v112, v112
	s_nop 0
	v_add_f32_e32 v112, 1.0, v112
	v_rcp_f32_e32 v140, v112
	v_mul_f32_e32 v112, 0xbfb8aa3b, v139
	v_exp_f32_e32 v112, v112
	s_nop 0
	v_add_f32_e32 v112, 1.0, v112
	v_rcp_f32_e32 v141, v112
	s_nop 0
	v_pk_mul_f32 v[138:139], v[138:139], v[140:141]
	v_pk_mul_f32 v[140:141], v[60:61], v[178:179] op_sel_hi:[1,0]
	v_cvt_pk_bf16_f32 v135, v138, v139
	v_mul_f32_e32 v112, 0xbfb8aa3b, v140
	v_exp_f32_e32 v112, v112
	s_nop 0
	v_add_f32_e32 v112, 1.0, v112
	v_rcp_f32_e32 v142, v112
	v_mul_f32_e32 v112, 0xbfb8aa3b, v141
	v_exp_f32_e32 v112, v112
	s_nop 0
	v_add_f32_e32 v112, 1.0, v112
	v_rcp_f32_e32 v143, v112
	s_nop 0
	v_pk_mul_f32 v[140:141], v[140:141], v[142:143]
	v_pk_mul_f32 v[142:143], v[62:63], v[178:179] op_sel_hi:[1,0]
	s_nop 0
	v_mul_f32_e32 v112, 0xbfb8aa3b, v142
	v_exp_f32_e32 v112, v112
	s_nop 0
	v_add_f32_e32 v112, 1.0, v112
	v_rcp_f32_e32 v144, v112
	v_mul_f32_e32 v112, 0xbfb8aa3b, v143
	v_exp_f32_e32 v112, v112
	s_nop 0
	v_add_f32_e32 v112, 1.0, v112
	v_rcp_f32_e32 v145, v112
	s_nop 0
	v_pk_mul_f32 v[142:143], v[142:143], v[144:145]
	v_pk_mul_f32 v[144:145], v[52:53], v[178:179] op_sel_hi:[1,0]
	s_nop 0
	v_mul_f32_e32 v112, 0xbfb8aa3b, v144
	v_exp_f32_e32 v112, v112
	s_nop 0
	v_add_f32_e32 v112, 1.0, v112
	v_rcp_f32_e32 v146, v112
	v_mul_f32_e32 v112, 0xbfb8aa3b, v145
	v_exp_f32_e32 v112, v112
	s_nop 0
	v_add_f32_e32 v112, 1.0, v112
	v_rcp_f32_e32 v147, v112
	s_nop 0
	v_pk_mul_f32 v[144:145], v[144:145], v[146:147]
	v_pk_mul_f32 v[146:147], v[54:55], v[178:179] op_sel_hi:[1,0]
	s_nop 0
	v_mul_f32_e32 v112, 0xbfb8aa3b, v146
	v_exp_f32_e32 v112, v112
	s_nop 0
	v_add_f32_e32 v112, 1.0, v112
	v_rcp_f32_e32 v148, v112
	v_mul_f32_e32 v112, 0xbfb8aa3b, v147
	v_exp_f32_e32 v112, v112
	s_nop 0
	v_add_f32_e32 v112, 1.0, v112
	v_rcp_f32_e32 v149, v112
	v_add_u32_e32 v112, s19, v181
	s_nop 0
	v_pk_mul_f32 v[146:147], v[146:147], v[148:149]
	v_ashrrev_i32_e32 v148, 31, v112
	s_nop 0
	v_mul_lo_u32 v148, s26, v112
	v_mov_b32_e64 v149, 0
	v_lshl_add_u64 v[148:149], v[148:149], 1, v[170:171]
	global_store_dwordx4 v[148:149], v[132:135], off
	s_nop 1
	v_cvt_pk_bf16_f32 v132, v140, v141
	v_cvt_pk_bf16_f32 v133, v142, v143
	v_cvt_pk_bf16_f32 v134, v144, v145
	v_cvt_pk_bf16_f32 v135, v146, v147
	global_store_dwordx4 v[148:149], v[132:135], off offset:64
	s_nop 1
	v_pk_mul_f32 v[132:133], v[40:41], v[176:177] op_sel_hi:[1,0]
	s_nop 0
	v_mul_f32_e32 v112, 0xbfb8aa3b, v132
	v_exp_f32_e32 v112, v112
	s_nop 0
	v_add_f32_e32 v112, 1.0, v112
	v_rcp_f32_e32 v134, v112
	v_mul_f32_e32 v112, 0xbfb8aa3b, v133
	v_exp_f32_e32 v112, v112
	s_nop 0
	v_add_f32_e32 v112, 1.0, v112
	v_rcp_f32_e32 v135, v112
	s_nop 0
	v_pk_mul_f32 v[132:133], v[132:133], v[134:135]
	v_pk_mul_f32 v[134:135], v[42:43], v[176:177] op_sel_hi:[1,0]
	v_cvt_pk_bf16_f32 v132, v132, v133
	v_mul_f32_e32 v112, 0xbfb8aa3b, v134
	v_exp_f32_e32 v112, v112
	s_nop 0
	v_add_f32_e32 v112, 1.0, v112
	v_rcp_f32_e32 v136, v112
	v_mul_f32_e32 v112, 0xbfb8aa3b, v135
	v_exp_f32_e32 v112, v112
	s_nop 0
	v_add_f32_e32 v112, 1.0, v112
	v_rcp_f32_e32 v137, v112
	s_nop 0
	v_pk_mul_f32 v[134:135], v[134:135], v[136:137]
	v_pk_mul_f32 v[136:137], v[32:33], v[176:177] op_sel_hi:[1,0]
	v_cvt_pk_bf16_f32 v133, v134, v135
	v_mul_f32_e32 v112, 0xbfb8aa3b, v136
	v_exp_f32_e32 v112, v112
	s_nop 0
	v_add_f32_e32 v112, 1.0, v112
	v_rcp_f32_e32 v138, v112
	v_mul_f32_e32 v112, 0xbfb8aa3b, v137
	v_exp_f32_e32 v112, v112
	s_nop 0
	v_add_f32_e32 v112, 1.0, v112
	v_rcp_f32_e32 v139, v112
	s_nop 0
	v_pk_mul_f32 v[136:137], v[136:137], v[138:139]
	v_pk_mul_f32 v[138:139], v[34:35], v[176:177] op_sel_hi:[1,0]
	v_cvt_pk_bf16_f32 v134, v136, v137
	v_mul_f32_e32 v112, 0xbfb8aa3b, v138
	v_exp_f32_e32 v112, v112
	s_nop 0
	v_add_f32_e32 v112, 1.0, v112
	v_rcp_f32_e32 v140, v112
	v_mul_f32_e32 v112, 0xbfb8aa3b, v139
	v_exp_f32_e32 v112, v112
	s_nop 0
	v_add_f32_e32 v112, 1.0, v112
	v_rcp_f32_e32 v141, v112
	s_nop 0
	v_pk_mul_f32 v[138:139], v[138:139], v[140:141]
	v_pk_mul_f32 v[140:141], v[44:45], v[176:177] op_sel_hi:[1,0]
	v_cvt_pk_bf16_f32 v135, v138, v139
	v_mul_f32_e32 v112, 0xbfb8aa3b, v140
	v_exp_f32_e32 v112, v112
	s_nop 0
	v_add_f32_e32 v112, 1.0, v112
	v_rcp_f32_e32 v142, v112
	v_mul_f32_e32 v112, 0xbfb8aa3b, v141
	v_exp_f32_e32 v112, v112
	s_nop 0
	v_add_f32_e32 v112, 1.0, v112
	v_rcp_f32_e32 v143, v112
	s_nop 0
	v_pk_mul_f32 v[140:141], v[140:141], v[142:143]
	v_pk_mul_f32 v[142:143], v[46:47], v[176:177] op_sel_hi:[1,0]
	s_nop 0
	v_mul_f32_e32 v112, 0xbfb8aa3b, v142
	v_exp_f32_e32 v112, v112
	s_nop 0
	v_add_f32_e32 v112, 1.0, v112
	v_rcp_f32_e32 v144, v112
	v_mul_f32_e32 v112, 0xbfb8aa3b, v143
	v_exp_f32_e32 v112, v112
	s_nop 0
	v_add_f32_e32 v112, 1.0, v112
	v_rcp_f32_e32 v145, v112
	s_nop 0
	v_pk_mul_f32 v[142:143], v[142:143], v[144:145]
	v_pk_mul_f32 v[144:145], v[36:37], v[176:177] op_sel_hi:[1,0]
	s_nop 0
	v_mul_f32_e32 v112, 0xbfb8aa3b, v144
	v_exp_f32_e32 v112, v112
	s_nop 0
	v_add_f32_e32 v112, 1.0, v112
	v_rcp_f32_e32 v146, v112
	v_mul_f32_e32 v112, 0xbfb8aa3b, v145
	v_exp_f32_e32 v112, v112
	s_nop 0
	v_add_f32_e32 v112, 1.0, v112
; __device__ __forceinline__ unsigned pkbf(float lo, float hi) { f32x2v v = {lo, hi}; return __builtin_bit_cast(unsigned, __builtin_convertvector(v, bf2_t)); }
;     template <int TYPE  >
;     __device__ __forceinline__ void rows(const pg8::f32x4 (&acc)[2][2][4][2], const pg8::Unit& u, int wr, int fr, int fq, const float (&rstd)[2][4], bf16_t* dst, int ld, const float* gain, float qs) const {
;     ...
; #pragma unroll
;                     for (int bj = 0; bj < 2; ++bj)
; #pragma unroll
;                         for (int n = 0; n < 2; ++n)
; #pragma unroll
;                             for (int e = 0; e < 4; ++e) { const float z = acc[ai][bj][m][n][e] * rstd[ai][m]; v[bj][n][e] = TYPE == 3 ? z * __builtin_amdgcn_rcpf(1.0f + __expf(-z)) : z; }
;                 }
;                 bf16_t* rowp = dst + (size_t)row * ld;
; #pragma unroll
;                 for (int bj = 0; bj < 2; ++bj) {
;                     u32x4 w; w.x = pkbf(v[bj][0][0], v[bj][0][1]); w.y = pkbf(v[bj][0][2], v[bj][0][3]); w.z = pkbf(v[bj][1][0], v[bj][1][1]); w.w = pkbf(v[bj][1][2], v[bj][1][3]);
;                     *(u32x4*)(rowp + 32 * bj) = w;
;                 }
	v_rcp_f32_e32 v147, v112
	s_nop 0
	v_pk_mul_f32 v[144:145], v[144:145], v[146:147]
	v_pk_mul_f32 v[146:147], v[38:39], v[176:177] op_sel_hi:[1,0]
	s_nop 0
	v_mul_f32_e32 v112, 0xbfb8aa3b, v146
	v_exp_f32_e32 v112, v112
	s_nop 0
	v_add_f32_e32 v112, 1.0, v112
	v_rcp_f32_e32 v148, v112
	v_mul_f32_e32 v112, 0xbfb8aa3b, v147
	v_exp_f32_e32 v112, v112
	s_nop 0
	v_add_f32_e32 v112, 1.0, v112
	v_rcp_f32_e32 v149, v112
	v_add_u32_e32 v112, s19, v183
	s_nop 0
	v_pk_mul_f32 v[146:147], v[146:147], v[148:149]
	v_ashrrev_i32_e32 v148, 31, v112
	s_nop 0
	v_mul_lo_u32 v148, s26, v112
	v_mov_b32_e64 v149, 0
	v_lshl_add_u64 v[148:149], v[148:149], 1, v[170:171]
	global_store_dwordx4 v[148:149], v[132:135], off
	s_nop 1
	v_cvt_pk_bf16_f32 v132, v140, v141
	v_cvt_pk_bf16_f32 v133, v142, v143
	v_cvt_pk_bf16_f32 v134, v144, v145
	v_cvt_pk_bf16_f32 v135, v146, v147
	global_store_dwordx4 v[148:149], v[132:135], off offset:64
	s_nop 1
	v_pk_mul_f32 v[132:133], v[24:25], v[174:175] op_sel_hi:[1,0]
	s_nop 0
	v_mul_f32_e32 v112, 0xbfb8aa3b, v132
	v_exp_f32_e32 v112, v112
	s_nop 0
	v_add_f32_e32 v112, 1.0, v112
	v_rcp_f32_e32 v134, v112
	v_mul_f32_e32 v112, 0xbfb8aa3b, v133
	v_exp_f32_e32 v112, v112
	s_nop 0
	v_add_f32_e32 v112, 1.0, v112
	v_rcp_f32_e32 v135, v112
	s_nop 0
	v_pk_mul_f32 v[132:133], v[132:133], v[134:135]
	v_pk_mul_f32 v[134:135], v[26:27], v[174:175] op_sel_hi:[1,0]
	v_cvt_pk_bf16_f32 v132, v132, v133
	v_mul_f32_e32 v112, 0xbfb8aa3b, v134
	v_exp_f32_e32 v112, v112
	s_nop 0
	v_add_f32_e32 v112, 1.0, v112
	v_rcp_f32_e32 v136, v112
	v_mul_f32_e32 v112, 0xbfb8aa3b, v135
	v_exp_f32_e32 v112, v112
	s_nop 0
	v_add_f32_e32 v112, 1.0, v112
	v_rcp_f32_e32 v137, v112
	s_nop 0
	v_pk_mul_f32 v[134:135], v[134:135], v[136:137]
	v_pk_mul_f32 v[136:137], v[16:17], v[174:175] op_sel_hi:[1,0]
	v_cvt_pk_bf16_f32 v133, v134, v135
	v_mul_f32_e32 v112, 0xbfb8aa3b, v136
	v_exp_f32_e32 v112, v112
	s_nop 0
	v_add_f32_e32 v112, 1.0, v112
	v_rcp_f32_e32 v138, v112
	v_mul_f32_e32 v112, 0xbfb8aa3b, v137
	v_exp_f32_e32 v112, v112
	s_nop 0
	v_add_f32_e32 v112, 1.0, v112
	v_rcp_f32_e32 v139, v112
	s_nop 0
	v_pk_mul_f32 v[136:137], v[136:137], v[138:139]
	v_pk_mul_f32 v[138:139], v[18:19], v[174:175] op_sel_hi:[1,0]
	v_cvt_pk_bf16_f32 v134, v136, v137
	v_mul_f32_e32 v112, 0xbfb8aa3b, v138
	v_exp_f32_e32 v112, v112
	s_nop 0
	v_add_f32_e32 v112, 1.0, v112
	v_rcp_f32_e32 v140, v112
	v_mul_f32_e32 v112, 0xbfb8aa3b, v139
	v_exp_f32_e32 v112, v112
	s_nop 0
	v_add_f32_e32 v112, 1.0, v112
	v_rcp_f32_e32 v141, v112
	s_nop 0
	v_pk_mul_f32 v[138:139], v[138:139], v[140:141]
	v_pk_mul_f32 v[140:141], v[28:29], v[174:175] op_sel_hi:[1,0]
	v_cvt_pk_bf16_f32 v135, v138, v139
	v_mul_f32_e32 v112, 0xbfb8aa3b, v140
	v_exp_f32_e32 v112, v112
	s_nop 0
	v_add_f32_e32 v112, 1.0, v112
	v_rcp_f32_e32 v142, v112
	v_mul_f32_e32 v112, 0xbfb8aa3b, v141
	v_exp_f32_e32 v112, v112
	s_nop 0
	v_add_f32_e32 v112, 1.0, v112
	v_rcp_f32_e32 v143, v112
	s_nop 0
	v_pk_mul_f32 v[140:141], v[140:141], v[142:143]
	v_pk_mul_f32 v[142:143], v[30:31], v[174:175] op_sel_hi:[1,0]
	s_nop 0
	v_mul_f32_e32 v112, 0xbfb8aa3b, v142
	v_exp_f32_e32 v112, v112
	s_nop 0
	v_add_f32_e32 v112, 1.0, v112
	v_rcp_f32_e32 v144, v112
	v_mul_f32_e32 v112, 0xbfb8aa3b, v143
	v_exp_f32_e32 v112, v112
	s_nop 0
	v_add_f32_e32 v112, 1.0, v112
	v_rcp_f32_e32 v145, v112
	s_nop 0
	v_pk_mul_f32 v[142:143], v[142:143], v[144:145]
	v_pk_mul_f32 v[144:145], v[20:21], v[174:175] op_sel_hi:[1,0]
	s_nop 0
	v_mul_f32_e32 v112, 0xbfb8aa3b, v144
	v_exp_f32_e32 v112, v112
	s_nop 0
	v_add_f32_e32 v112, 1.0, v112
	v_rcp_f32_e32 v146, v112
	v_mul_f32_e32 v112, 0xbfb8aa3b, v145
	v_exp_f32_e32 v112, v112
	s_nop 0
	v_add_f32_e32 v112, 1.0, v112
	v_rcp_f32_e32 v147, v112
	s_nop 0
	v_pk_mul_f32 v[144:145], v[144:145], v[146:147]
	v_pk_mul_f32 v[146:147], v[22:23], v[174:175] op_sel_hi:[1,0]
	s_nop 0
	v_mul_f32_e32 v112, 0xbfb8aa3b, v146
	v_exp_f32_e32 v112, v112
	s_nop 0
	v_add_f32_e32 v112, 1.0, v112
	v_rcp_f32_e32 v148, v112
	v_mul_f32_e32 v112, 0xbfb8aa3b, v147
	v_exp_f32_e32 v112, v112
	s_nop 0
	v_add_f32_e32 v112, 1.0, v112
	v_rcp_f32_e32 v149, v112
	v_add_u32_e32 v112, s19, v185
	s_nop 0
	v_pk_mul_f32 v[146:147], v[146:147], v[148:149]
	v_ashrrev_i32_e32 v148, 31, v112
	s_nop 0
	v_mul_lo_u32 v148, s26, v112
	v_mov_b32_e64 v149, 0
	v_lshl_add_u64 v[148:149], v[148:149], 1, v[170:171]
	global_store_dwordx4 v[148:149], v[132:135], off
	s_mov_b64 s[34:35], 0
	s_nop 0
	v_cvt_pk_bf16_f32 v132, v140, v141
	v_cvt_pk_bf16_f32 v133, v142, v143
	v_cvt_pk_bf16_f32 v134, v144, v145
	v_cvt_pk_bf16_f32 v135, v146, v147
	global_store_dwordx4 v[148:149], v[132:135], off offset:64
	s_nop 1
	v_pk_mul_f32 v[132:133], v[12:13], v[172:173] op_sel_hi:[1,0]
	s_nop 0
	v_mul_f32_e32 v112, 0xbfb8aa3b, v132
	v_exp_f32_e32 v112, v112
	s_nop 0
	v_add_f32_e32 v112, 1.0, v112
	v_rcp_f32_e32 v134, v112
	v_mul_f32_e32 v112, 0xbfb8aa3b, v133
	v_exp_f32_e32 v112, v112
	s_nop 0
	v_add_f32_e32 v112, 1.0, v112
	v_rcp_f32_e32 v135, v112
	s_nop 0
	v_pk_mul_f32 v[132:133], v[132:133], v[134:135]
	v_pk_mul_f32 v[134:135], v[14:15], v[172:173] op_sel_hi:[1,0]
	s_nop 0
	v_mul_f32_e32 v112, 0xbfb8aa3b, v134
	v_exp_f32_e32 v112, v112
	s_nop 0
	v_add_f32_e32 v112, 1.0, v112
	v_rcp_f32_e32 v136, v112
	v_mul_f32_e32 v112, 0xbfb8aa3b, v135
	v_exp_f32_e32 v112, v112
	s_nop 0
	v_add_f32_e32 v112, 1.0, v112
	v_rcp_f32_e32 v137, v112
	s_nop 0
	v_pk_mul_f32 v[134:135], v[134:135], v[136:137]
	v_pk_mul_f32 v[136:137], v[8:9], v[172:173] op_sel_hi:[1,0]
	s_nop 0
	v_mul_f32_e32 v112, 0xbfb8aa3b, v136
	v_exp_f32_e32 v112, v112
	s_nop 0
	v_add_f32_e32 v112, 1.0, v112
	v_rcp_f32_e32 v138, v112
	v_mul_f32_e32 v112, 0xbfb8aa3b, v137
; __device__ __forceinline__ unsigned pkbf(float lo, float hi) { f32x2v v = {lo, hi}; return __builtin_bit_cast(unsigned, __builtin_convertvector(v, bf2_t)); }
;     template <int TYPE  >
;     __device__ __forceinline__ void rows(const pg8::f32x4 (&acc)[2][2][4][2], const pg8::Unit& u, int wr, int fr, int fq, const float (&rstd)[2][4], bf16_t* dst, int ld, const float* gain, float qs) const {
;     ...
; #pragma unroll
;                     for (int bj = 0; bj < 2; ++bj)
; #pragma unroll
;                         for (int n = 0; n < 2; ++n)
; #pragma unroll
;                             for (int e = 0; e < 4; ++e) { const float z = acc[ai][bj][m][n][e] * rstd[ai][m]; v[bj][n][e] = TYPE == 3 ? z * __builtin_amdgcn_rcpf(1.0f + __expf(-z)) : z; }
;                 }
;                 bf16_t* rowp = dst + (size_t)row * ld;
; #pragma unroll
;                 for (int bj = 0; bj < 2; ++bj) {
;                     u32x4 w; w.x = pkbf(v[bj][0][0], v[bj][0][1]); w.y = pkbf(v[bj][0][2], v[bj][0][3]); w.z = pkbf(v[bj][1][0], v[bj][1][1]); w.w = pkbf(v[bj][1][2], v[bj][1][3]);
;                     *(u32x4*)(rowp + 32 * bj) = w;
;                 }
	v_exp_f32_e32 v112, v112
	s_nop 0
	v_add_f32_e32 v112, 1.0, v112
	v_rcp_f32_e32 v139, v112
	s_nop 0
	v_pk_mul_f32 v[136:137], v[136:137], v[138:139]
	v_pk_mul_f32 v[138:139], v[10:11], v[172:173] op_sel_hi:[1,0]
	s_nop 0
	v_mul_f32_e32 v112, 0xbfb8aa3b, v138
	v_exp_f32_e32 v112, v112
	s_nop 0
	v_add_f32_e32 v112, 1.0, v112
	v_rcp_f32_e32 v140, v112
	v_mul_f32_e32 v112, 0xbfb8aa3b, v139
	v_exp_f32_e32 v112, v112
	s_nop 0
	v_add_f32_e32 v112, 1.0, v112
	v_rcp_f32_e32 v141, v112
	s_nop 0
	v_pk_mul_f32 v[138:139], v[138:139], v[140:141]
	v_pk_mul_f32 v[140:141], v[4:5], v[172:173] op_sel_hi:[1,0]
	s_nop 0
	v_mul_f32_e32 v112, 0xbfb8aa3b, v140
	v_exp_f32_e32 v112, v112
	s_nop 0
	v_add_f32_e32 v112, 1.0, v112
	v_rcp_f32_e32 v142, v112
	v_mul_f32_e32 v112, 0xbfb8aa3b, v141
	v_exp_f32_e32 v112, v112
	s_nop 0
	v_add_f32_e32 v112, 1.0, v112
	v_rcp_f32_e32 v143, v112
	s_nop 0
	v_pk_mul_f32 v[140:141], v[140:141], v[142:143]
	v_pk_mul_f32 v[142:143], v[6:7], v[172:173] op_sel_hi:[1,0]
	s_nop 0
	v_mul_f32_e32 v112, 0xbfb8aa3b, v142
	v_exp_f32_e32 v112, v112
	s_nop 0
	v_add_f32_e32 v112, 1.0, v112
	v_rcp_f32_e32 v144, v112
	v_mul_f32_e32 v112, 0xbfb8aa3b, v143
	v_exp_f32_e32 v112, v112
	s_nop 0
	v_add_f32_e32 v112, 1.0, v112
	v_rcp_f32_e32 v145, v112
	s_nop 0
	v_pk_mul_f32 v[142:143], v[142:143], v[144:145]
	v_pk_mul_f32 v[144:145], v[0:1], v[172:173] op_sel_hi:[1,0]
	s_nop 0
	v_mul_f32_e32 v112, 0xbfb8aa3b, v144
	v_exp_f32_e32 v112, v112
	s_nop 0
	v_add_f32_e32 v112, 1.0, v112
	v_rcp_f32_e32 v146, v112
	v_mul_f32_e32 v112, 0xbfb8aa3b, v145
	v_exp_f32_e32 v112, v112
	s_nop 0
	v_add_f32_e32 v112, 1.0, v112
	v_rcp_f32_e32 v147, v112
	s_nop 0
	v_pk_mul_f32 v[144:145], v[144:145], v[146:147]
	v_pk_mul_f32 v[146:147], v[2:3], v[172:173] op_sel_hi:[1,0]
	s_nop 0
	v_mul_f32_e32 v112, 0xbfb8aa3b, v146
	v_exp_f32_e32 v112, v112
	s_nop 0
	v_add_f32_e32 v112, 1.0, v112
	v_rcp_f32_e32 v148, v112
	v_mul_f32_e32 v112, 0xbfb8aa3b, v147
	v_exp_f32_e32 v112, v112
	s_nop 0
	v_add_f32_e32 v112, 1.0, v112
	v_rcp_f32_e32 v149, v112
	s_nop 0
	v_pk_mul_f32 v[146:147], v[146:147], v[148:149]
	v_add_u32_e32 v148, s19, v191
.LBB0_332:
	s_andn2_b64 vcc, exec, s[34:35]
	s_cbranch_vccnz .LBB0_334
	s_nop 0
	s_nop 0
	v_mul_lo_u32 v146, s26, v192
	v_pk_mul_f32 v[132:133], v[120:121], v[190:191] op_sel_hi:[1,0]
	v_pk_mul_f32 v[134:135], v[114:115], v[190:191] op_sel_hi:[1,0]
	v_pk_mul_f32 v[136:137], v[116:117], v[190:191] op_sel_hi:[1,0]
	v_mov_b32_e64 v147, 0
	v_pk_mul_f32 v[138:139], v[126:127], v[190:191] op_sel_hi:[1,0]
	v_pk_mul_f32 v[140:141], v[128:129], v[190:191] op_sel_hi:[1,0]
	v_pk_mul_f32 v[142:143], v[122:123], v[190:191] op_sel_hi:[1,0]
	v_pk_mul_f32 v[144:145], v[124:125], v[190:191] op_sel_hi:[1,0]
	v_lshl_add_u64 v[146:147], v[146:147], 1, v[170:171]
	v_cvt_pk_bf16_f32 v130, v130, v131
	v_cvt_pk_bf16_f32 v131, v132, v133
	v_cvt_pk_bf16_f32 v132, v134, v135
	v_cvt_pk_bf16_f32 v133, v136, v137
	global_store_dwordx4 v[146:147], v[130:133], off
	v_add_u32_e32 v112, s19, v175
	s_nop 0
	v_cvt_pk_bf16_f32 v130, v138, v139
	v_cvt_pk_bf16_f32 v131, v140, v141
	v_cvt_pk_bf16_f32 v132, v142, v143
	v_cvt_pk_bf16_f32 v133, v144, v145
	global_store_dwordx4 v[146:147], v[130:133], off offset:64
	v_ashrrev_i32_e32 v146, 31, v112
	s_nop 0
	v_mul_lo_u32 v146, s26, v112
	v_pk_mul_f32 v[130:131], v[104:105], v[184:185] op_sel_hi:[1,0]
	v_pk_mul_f32 v[132:133], v[106:107], v[184:185] op_sel_hi:[1,0]
	v_pk_mul_f32 v[134:135], v[96:97], v[184:185] op_sel_hi:[1,0]
	v_pk_mul_f32 v[136:137], v[98:99], v[184:185] op_sel_hi:[1,0]
	v_mov_b32_e64 v147, 0
	v_pk_mul_f32 v[138:139], v[108:109], v[184:185] op_sel_hi:[1,0]
	v_pk_mul_f32 v[140:141], v[110:111], v[184:185] op_sel_hi:[1,0]
	v_pk_mul_f32 v[142:143], v[100:101], v[184:185] op_sel_hi:[1,0]
	v_pk_mul_f32 v[144:145], v[102:103], v[184:185] op_sel_hi:[1,0]
	v_lshl_add_u64 v[146:147], v[146:147], 1, v[170:171]
	v_cvt_pk_bf16_f32 v130, v130, v131
	v_cvt_pk_bf16_f32 v131, v132, v133
	v_cvt_pk_bf16_f32 v132, v134, v135
	v_cvt_pk_bf16_f32 v133, v136, v137
	global_store_dwordx4 v[146:147], v[130:133], off
	v_add_u32_e32 v112, s19, v177
	s_nop 0
	v_cvt_pk_bf16_f32 v130, v138, v139
	v_cvt_pk_bf16_f32 v131, v140, v141
	v_cvt_pk_bf16_f32 v132, v142, v143
	v_cvt_pk_bf16_f32 v133, v144, v145
	global_store_dwordx4 v[146:147], v[130:133], off offset:64
	v_ashrrev_i32_e32 v146, 31, v112
	s_nop 0
	v_mul_lo_u32 v146, s26, v112
	v_pk_mul_f32 v[130:131], v[88:89], v[182:183] op_sel_hi:[1,0]
	v_pk_mul_f32 v[132:133], v[90:91], v[182:183] op_sel_hi:[1,0]
	v_pk_mul_f32 v[134:135], v[80:81], v[182:183] op_sel_hi:[1,0]
	v_pk_mul_f32 v[136:137], v[82:83], v[182:183] op_sel_hi:[1,0]
	v_mov_b32_e64 v147, 0
	v_pk_mul_f32 v[138:139], v[92:93], v[182:183] op_sel_hi:[1,0]
	v_pk_mul_f32 v[140:141], v[94:95], v[182:183] op_sel_hi:[1,0]
	v_pk_mul_f32 v[142:143], v[84:85], v[182:183] op_sel_hi:[1,0]
	v_pk_mul_f32 v[144:145], v[86:87], v[182:183] op_sel_hi:[1,0]
	v_lshl_add_u64 v[146:147], v[146:147], 1, v[170:171]
	v_cvt_pk_bf16_f32 v130, v130, v131
	v_cvt_pk_bf16_f32 v131, v132, v133
	v_cvt_pk_bf16_f32 v132, v134, v135
	v_cvt_pk_bf16_f32 v133, v136, v137
; __device__ __forceinline__ unsigned pkbf(float lo, float hi) { f32x2v v = {lo, hi}; return __builtin_bit_cast(unsigned, __builtin_convertvector(v, bf2_t)); }
;     template <int TYPE  >
;     __device__ __forceinline__ void rows(const pg8::f32x4 (&acc)[2][2][4][2], const pg8::Unit& u, int wr, int fr, int fq, const float (&rstd)[2][4], bf16_t* dst, int ld, const float* gain, float qs) const {
;     ...
; #pragma unroll
;                     for (int bj = 0; bj < 2; ++bj)
; #pragma unroll
;                         for (int n = 0; n < 2; ++n)
; #pragma unroll
;                             for (int e = 0; e < 4; ++e) { const float z = acc[ai][bj][m][n][e] * rstd[ai][m]; v[bj][n][e] = TYPE == 3 ? z * __builtin_amdgcn_rcpf(1.0f + __expf(-z)) : z; }
;                 }
;                 bf16_t* rowp = dst + (size_t)row * ld;
; #pragma unroll
;                 for (int bj = 0; bj < 2; ++bj) {
;                     u32x4 w; w.x = pkbf(v[bj][0][0], v[bj][0][1]); w.y = pkbf(v[bj][0][2], v[bj][0][3]); w.z = pkbf(v[bj][1][0], v[bj][1][1]); w.w = pkbf(v[bj][1][2], v[bj][1][3]);
;                     *(u32x4*)(rowp + 32 * bj) = w;
;                 }
	global_store_dwordx4 v[146:147], v[130:133], off
	v_add_u32_e32 v112, s19, v179
	s_nop 0
	v_cvt_pk_bf16_f32 v130, v138, v139
	v_cvt_pk_bf16_f32 v131, v140, v141
	v_cvt_pk_bf16_f32 v132, v142, v143
	v_cvt_pk_bf16_f32 v133, v144, v145
	global_store_dwordx4 v[146:147], v[130:133], off offset:64
	v_ashrrev_i32_e32 v146, 31, v112
	s_nop 0
	v_mul_lo_u32 v146, s26, v112
	v_pk_mul_f32 v[130:131], v[72:73], v[180:181] op_sel_hi:[1,0]
	v_pk_mul_f32 v[132:133], v[74:75], v[180:181] op_sel_hi:[1,0]
	v_pk_mul_f32 v[134:135], v[64:65], v[180:181] op_sel_hi:[1,0]
	v_pk_mul_f32 v[136:137], v[66:67], v[180:181] op_sel_hi:[1,0]
	v_mov_b32_e64 v147, 0
	v_pk_mul_f32 v[138:139], v[76:77], v[180:181] op_sel_hi:[1,0]
	v_pk_mul_f32 v[140:141], v[78:79], v[180:181] op_sel_hi:[1,0]
	v_pk_mul_f32 v[142:143], v[68:69], v[180:181] op_sel_hi:[1,0]
	v_pk_mul_f32 v[144:145], v[70:71], v[180:181] op_sel_hi:[1,0]
	v_lshl_add_u64 v[146:147], v[146:147], 1, v[170:171]
	v_cvt_pk_bf16_f32 v130, v130, v131
	v_cvt_pk_bf16_f32 v131, v132, v133
	v_cvt_pk_bf16_f32 v132, v134, v135
	v_cvt_pk_bf16_f32 v133, v136, v137
	global_store_dwordx4 v[146:147], v[130:133], off
	v_add_u32_e32 v112, s19, v181
	s_nop 0
	v_cvt_pk_bf16_f32 v130, v138, v139
	v_cvt_pk_bf16_f32 v131, v140, v141
	v_cvt_pk_bf16_f32 v132, v142, v143
	v_cvt_pk_bf16_f32 v133, v144, v145
	global_store_dwordx4 v[146:147], v[130:133], off offset:64
	v_ashrrev_i32_e32 v146, 31, v112
	s_nop 0
	v_mul_lo_u32 v146, s26, v112
	v_pk_mul_f32 v[130:131], v[56:57], v[178:179] op_sel_hi:[1,0]
	v_pk_mul_f32 v[132:133], v[58:59], v[178:179] op_sel_hi:[1,0]
	v_pk_mul_f32 v[134:135], v[48:49], v[178:179] op_sel_hi:[1,0]
	v_pk_mul_f32 v[136:137], v[50:51], v[178:179] op_sel_hi:[1,0]
	v_mov_b32_e64 v147, 0
	v_pk_mul_f32 v[138:139], v[60:61], v[178:179] op_sel_hi:[1,0]
	v_pk_mul_f32 v[140:141], v[62:63], v[178:179] op_sel_hi:[1,0]
	v_pk_mul_f32 v[142:143], v[52:53], v[178:179] op_sel_hi:[1,0]
	v_pk_mul_f32 v[144:145], v[54:55], v[178:179] op_sel_hi:[1,0]
	v_lshl_add_u64 v[146:147], v[146:147], 1, v[170:171]
	v_cvt_pk_bf16_f32 v130, v130, v131
	v_cvt_pk_bf16_f32 v131, v132, v133
	v_cvt_pk_bf16_f32 v132, v134, v135
	v_cvt_pk_bf16_f32 v133, v136, v137
	global_store_dwordx4 v[146:147], v[130:133], off
	v_add_u32_e32 v112, s19, v183
	s_nop 0
	v_cvt_pk_bf16_f32 v130, v138, v139
	v_cvt_pk_bf16_f32 v131, v140, v141
	v_cvt_pk_bf16_f32 v132, v142, v143
	v_cvt_pk_bf16_f32 v133, v144, v145
	global_store_dwordx4 v[146:147], v[130:133], off offset:64
	v_ashrrev_i32_e32 v146, 31, v112
	s_nop 0
	v_mul_lo_u32 v146, s26, v112
	v_pk_mul_f32 v[130:131], v[40:41], v[176:177] op_sel_hi:[1,0]
	v_pk_mul_f32 v[132:133], v[42:43], v[176:177] op_sel_hi:[1,0]
	v_pk_mul_f32 v[134:135], v[32:33], v[176:177] op_sel_hi:[1,0]
	v_pk_mul_f32 v[136:137], v[34:35], v[176:177] op_sel_hi:[1,0]
	v_mov_b32_e64 v147, 0
	v_pk_mul_f32 v[138:139], v[44:45], v[176:177] op_sel_hi:[1,0]
	v_pk_mul_f32 v[140:141], v[46:47], v[176:177] op_sel_hi:[1,0]
	v_pk_mul_f32 v[142:143], v[36:37], v[176:177] op_sel_hi:[1,0]
	v_pk_mul_f32 v[144:145], v[38:39], v[176:177] op_sel_hi:[1,0]
	v_lshl_add_u64 v[146:147], v[146:147], 1, v[170:171]
	v_cvt_pk_bf16_f32 v130, v130, v131
	v_cvt_pk_bf16_f32 v131, v132, v133
	v_cvt_pk_bf16_f32 v132, v134, v135
	v_cvt_pk_bf16_f32 v133, v136, v137
	global_store_dwordx4 v[146:147], v[130:133], off
	v_add_u32_e32 v112, s19, v185
	s_nop 0
	v_cvt_pk_bf16_f32 v130, v138, v139
	v_cvt_pk_bf16_f32 v131, v140, v141
	v_cvt_pk_bf16_f32 v132, v142, v143
	v_cvt_pk_bf16_f32 v133, v144, v145
	global_store_dwordx4 v[146:147], v[130:133], off offset:64
	v_ashrrev_i32_e32 v146, 31, v112
	s_nop 0
	v_mul_lo_u32 v146, s26, v112
	v_pk_mul_f32 v[130:131], v[24:25], v[174:175] op_sel_hi:[1,0]
	v_pk_mul_f32 v[132:133], v[26:27], v[174:175] op_sel_hi:[1,0]
	v_pk_mul_f32 v[134:135], v[16:17], v[174:175] op_sel_hi:[1,0]
	v_pk_mul_f32 v[136:137], v[18:19], v[174:175] op_sel_hi:[1,0]
	v_mov_b32_e64 v147, 0
	v_pk_mul_f32 v[138:139], v[28:29], v[174:175] op_sel_hi:[1,0]
	v_pk_mul_f32 v[140:141], v[30:31], v[174:175] op_sel_hi:[1,0]
	v_pk_mul_f32 v[142:143], v[20:21], v[174:175] op_sel_hi:[1,0]
	v_pk_mul_f32 v[144:145], v[22:23], v[174:175] op_sel_hi:[1,0]
	v_lshl_add_u64 v[146:147], v[146:147], 1, v[170:171]
	v_cvt_pk_bf16_f32 v130, v130, v131
	v_cvt_pk_bf16_f32 v131, v132, v133
	v_cvt_pk_bf16_f32 v132, v134, v135
	v_cvt_pk_bf16_f32 v133, v136, v137
	global_store_dwordx4 v[146:147], v[130:133], off
	v_pk_mul_f32 v[134:135], v[14:15], v[172:173] op_sel_hi:[1,0]
	v_pk_mul_f32 v[136:137], v[8:9], v[172:173] op_sel_hi:[1,0]
	v_cvt_pk_bf16_f32 v130, v138, v139
	v_cvt_pk_bf16_f32 v131, v140, v141
	v_cvt_pk_bf16_f32 v132, v142, v143
	v_cvt_pk_bf16_f32 v133, v144, v145
	global_store_dwordx4 v[146:147], v[130:133], off offset:64
	v_pk_mul_f32 v[138:139], v[10:11], v[172:173] op_sel_hi:[1,0]
	v_pk_mul_f32 v[140:141], v[4:5], v[172:173] op_sel_hi:[1,0]
	v_pk_mul_f32 v[132:133], v[12:13], v[172:173] op_sel_hi:[1,0]
	v_pk_mul_f32 v[142:143], v[6:7], v[172:173] op_sel_hi:[1,0]
	v_pk_mul_f32 v[144:145], v[0:1], v[172:173] op_sel_hi:[1,0]
	v_pk_mul_f32 v[146:147], v[2:3], v[172:173] op_sel_hi:[1,0]
	v_add_u32_e32 v148, s19, v191

;     template <int TYPE  >
;     __device__ __forceinline__ void rows(const pg8::f32x4 (&acc)[2][2][4][2], const pg8::Unit& u, int wr, int fr, int fq, const float (&rstd)[2][4], bf16_t* dst, int ld, const float* gain, float qs) const {
;     ...
;                 const int row = u.pm * 256 + ai * 128 + wr * 64 + m * 16 + fr;
;                 float v[2][2][4];
;                 if (TYPE == 0) {
;                     float ss = 0.f;
; #pragma unroll
;                     for (int bj = 0; bj < 2; ++bj)
; #pragma unroll
;                         for (int n = 0; n < 2; ++n)
; #pragma unroll
;                             for (int e = 0; e < 4; ++e) ss += acc[ai][bj][m][n][e] * acc[ai][bj][m][n][e];
;                     ss = sum_fq(ss);
;                     const float r1 = rstd[ai][m], sc = r1 * __builtin_amdgcn_rsqf(r1 * r1 * ss * (1.0f / 64.0f) + EPS);
; #pragma unroll
;                     for (int bj = 0; bj < 2; ++bj)
; #pragma unroll
;                         for (int n = 0; n < 2; ++n)
; #pragma unroll
;                             for (int e = 0; e < 4; ++e) v[bj][n][e] = acc[ai][bj][m][n][e] * sc * gn[bj][n][e];
;                     const float* rp = rope + (size_t)(row & (SEQ - 1)) * 16 + 4 * (fq & 1);
;                     const f32x4 cs = *(const f32x4*)rp, sn = *(const f32x4*)(rp + 8);
; #pragma unroll
;                     for (int e = 0; e < 4; ++e) {
;                         const float t1 = v[0][0][e], t2 = v[0][1][e];
;                         const float o1 = t1 * cs[e] - t2 * sn[e], o2 = t2 * cs[e] + t1 * sn[e];
;                         v[0][0][e] = fq < 2 ? o1 : t1; v[0][1][e] = fq < 2 ? o2 : t2;
;                     }
;                 } else {
; #pragma unroll
;                     for (int bj = 0; bj < 2; ++bj)
; #pragma unroll
;                         for (int n = 0; n < 2; ++n)
; #pragma unroll
;                             for (int e = 0; e < 4; ++e) { const float z = acc[ai][bj][m][n][e] * rstd[ai][m]; v[bj][n][e] = TYPE == 3 ? z * __builtin_amdgcn_rcpf(1.0f + __expf(-z)) : z; }
;                 }
;                 bf16_t* rowp = dst + (size_t)row * ld;
; #pragma unroll
;                 for (int bj = 0; bj < 2; ++bj) {
;                     u32x4 w; w.x = pkbf(v[bj][0][0], v[bj][0][1]); w.y = pkbf(v[bj][0][2], v[bj][0][3]); w.z = pkbf(v[bj][1][0], v[bj][1][1]); w.w = pkbf(v[bj][1][2], v[bj][1][3]);
.LBB0_335:
	s_andn2_b64 vcc, exec, s[34:35]
	s_cbranch_vccnz .LBB0_337
	v_lshlrev_b32_e32 v112, 6, v192
	global_load_dwordx4 v[150:153], v205, s[30:31] offset:128
	global_load_dwordx4 v[146:149], v205, s[30:31] offset:144
	global_load_dwordx4 v[134:137], v203, s[30:31]
	global_load_dwordx4 v[130:133], v204, s[30:31]
	v_and_b32_e32 v112, 0x3f3c0, v112
	v_lshl_add_u64 v[142:143], v[164:165], 0, v[112:113]
	global_load_dwordx4 v[138:141], v[142:143], off
	s_nop 0
	global_load_dwordx4 v[142:145], v[142:143], off offset:32
	v_mul_f32_e32 v112, v119, v119
	v_fmac_f32_e32 v112, v118, v118
	v_fmac_f32_e32 v112, v120, v120
	v_fmac_f32_e32 v112, v121, v121
	v_fmac_f32_e32 v112, v114, v114
	v_fmac_f32_e32 v112, v115, v115
	v_fmac_f32_e32 v112, v116, v116
	v_fmac_f32_e32 v112, v117, v117
	v_fmac_f32_e32 v112, v126, v126
	v_fmac_f32_e32 v112, v127, v127
	v_fmac_f32_e32 v112, v128, v128
	v_fmac_f32_e32 v112, v129, v129
	v_fmac_f32_e32 v112, v122, v122
	v_fmac_f32_e32 v112, v123, v123
	v_fmac_f32_e32 v112, v124, v124
	s_nop 0
	s_nop 0
	v_mul_lo_u32 v192, s26, v192
	v_fmac_f32_e32 v112, v125, v125
	v_mov_b32_e64 v193, 0
	v_mov_b32_e32 v207, v112
	s_nop 1
	v_permlane16_swap_b32_e32 v112, v207
	v_add_f32_e32 v112, v112, v207
	v_mov_b32_e32 v207, v112
	s_nop 1
	v_permlane32_swap_b32_e32 v112, v207
	v_mul_f32_e32 v194, v190, v190
	v_add_f32_e32 v112, v112, v207
	v_mul_f32_e32 v112, v194, v112
	v_fmamk_f32 v112, v112, 0x3c800000, v198
	v_rsq_f32_e32 v207, v112
	v_add_u32_e32 v206, s19, v175
	v_lshlrev_b32_e32 v195, 6, v206
	v_and_b32_e32 v112, 0x3f7c0, v195
	v_lshl_add_u64 v[194:195], v[164:165], 0, v[112:113]
	v_mul_f32_e32 v112, v190, v207
	v_pk_mul_f32 v[208:209], v[126:127], v[112:113] op_sel_hi:[1,0]
	v_pk_mul_f32 v[210:211], v[128:129], v[112:113] op_sel_hi:[1,0]
	v_pk_mul_f32 v[212:213], v[122:123], v[112:113] op_sel_hi:[1,0]
	v_pk_mul_f32 v[214:215], v[124:125], v[112:113] op_sel_hi:[1,0]
	v_pk_mul_f32 v[216:217], v[118:119], v[112:113] op_sel_hi:[1,0]
	v_pk_mul_f32 v[218:219], v[114:115], v[112:113] op_sel_hi:[1,0]
	v_lshl_add_u64 v[192:193], v[192:193], 1, v[170:171]
	v_pk_mul_f32 v[120:121], v[120:121], v[112:113] op_sel_hi:[1,0]
	v_pk_mul_f32 v[116:117], v[116:117], v[112:113] op_sel_hi:[1,0]
	s_waitcnt vmcnt(5)
	v_pk_mul_f32 v[128:129], s[28:29], v[150:151] op_sel_hi:[0,1]
	v_pk_mul_f32 v[126:127], s[28:29], v[152:153] op_sel_hi:[0,1]
	s_waitcnt vmcnt(4)
	v_pk_mul_f32 v[124:125], s[28:29], v[146:147] op_sel_hi:[0,1]
	v_pk_mul_f32 v[122:123], s[28:29], v[148:149] op_sel_hi:[0,1]
	s_waitcnt vmcnt(3)
	v_pk_mul_f32 v[118:119], s[28:29], v[134:135] op_sel_hi:[0,1]
	s_waitcnt vmcnt(2)
	v_pk_mul_f32 v[114:115], s[28:29], v[130:131] op_sel_hi:[0,1]
	v_pk_mul_f32 v[130:131], v[128:129], v[208:209]
	v_pk_mul_f32 v[134:135], v[126:127], v[210:211]
	v_pk_mul_f32 v[148:149], v[124:125], v[212:213]
	v_pk_mul_f32 v[150:151], v[122:123], v[214:215]
	v_pk_mul_f32 v[152:153], v[118:119], v[216:217]
	v_pk_mul_f32 v[208:209], v[114:115], v[218:219]
	v_cvt_pk_bf16_f32 v146, v130, v131
	v_cvt_pk_bf16_f32 v147, v134, v135
	v_cvt_pk_bf16_f32 v148, v148, v149
	v_cvt_pk_bf16_f32 v149, v150, v151
	v_mov_b32_e32 v130, v152
	v_mov_b32_e32 v131, v208
	v_mov_b32_e32 v134, v153
	v_mov_b32_e32 v135, v209
	global_store_dwordx4 v[192:193], v[146:149], off offset:64
	v_pk_mul_f32 v[132:133], s[28:29], v[132:133] op_sel_hi:[0,1]
	v_pk_mul_f32 v[116:117], v[132:133], v[116:117]
	s_waitcnt vmcnt(2)
	v_mov_b32_e32 v146, v138
	s_waitcnt vmcnt(1)
	v_mov_b32_e32 v147, v142
	v_mov_b32_e32 v148, v139
	v_mov_b32_e32 v149, v143
	v_pk_mul_f32 v[130:131], v[146:147], v[130:131]
	v_pk_mul_f32 v[134:135], v[148:149], v[134:135]
	v_sub_f32_e32 v130, v130, v131
	v_sub_f32_e32 v131, v134, v135
	v_pk_mul_f32 v[138:139], v[138:139], v[208:209]
	v_cndmask_b32_e64 v130, v152, v130, s[38:39]
	v_cndmask_b32_e64 v131, v153, v131, s[38:39]
	v_pk_fma_f32 v[138:139], v[142:143], v[152:153], v[138:139]
	v_cvt_pk_bf16_f32 v146, v130, v131
	v_pk_mul_f32 v[130:131], s[28:29], v[136:137] op_sel_hi:[0,1]
	v_cndmask_b32_e64 v134, v209, v139, s[38:39]
	v_cndmask_b32_e64 v135, v208, v138, s[38:39]
	v_pk_mul_f32 v[120:121], v[130:131], v[120:121]
	v_cvt_pk_bf16_f32 v148, v135, v134
	v_mov_b32_e32 v134, v140
	v_mov_b32_e32 v135, v144
	v_mov_b32_e32 v136, v120
	v_mov_b32_e32 v137, v116
	v_pk_mul_f32 v[134:135], v[134:135], v[136:137]
	v_mov_b32_e32 v136, v121
	v_sub_f32_e32 v112, v134, v135
	v_mov_b32_e32 v134, v141
	v_mov_b32_e32 v135, v145
	v_mov_b32_e32 v137, v117
	v_pk_mul_f32 v[134:135], v[134:135], v[136:137]
	v_cndmask_b32_e64 v112, v120, v112, s[38:39]
	v_sub_f32_e32 v136, v134, v135
	v_pk_mul_f32 v[134:135], v[140:141], v[116:117]
	s_nop 0
	v_pk_fma_f32 v[134:135], v[144:145], v[120:121], v[134:135]
	v_cndmask_b32_e64 v120, v121, v136, s[38:39]
	v_cndmask_b32_e64 v117, v117, v135, s[38:39]
	v_cndmask_b32_e64 v116, v116, v134, s[38:39]
	v_cvt_pk_bf16_f32 v147, v112, v120
	v_cvt_pk_bf16_f32 v149, v116, v117
	global_store_dwordx4 v[192:193], v[146:149], off
	global_load_dwordx4 v[134:137], v[194:195], off
	global_load_dwordx4 v[138:141], v[194:195], off offset:32
	v_mul_f32_e32 v112, v105, v105
	v_fmac_f32_e32 v112, v104, v104
	v_fmac_f32_e32 v112, v106, v106
	v_fmac_f32_e32 v112, v107, v107
	v_fmac_f32_e32 v112, v96, v96
	v_fmac_f32_e32 v112, v97, v97
	v_fmac_f32_e32 v112, v98, v98
	v_fmac_f32_e32 v112, v99, v99
	v_fmac_f32_e32 v112, v108, v108
	v_fmac_f32_e32 v112, v109, v109
	v_fmac_f32_e32 v112, v110, v110
	v_fmac_f32_e32 v112, v111, v111
	v_fmac_f32_e32 v112, v100, v100
	v_fmac_f32_e32 v112, v101, v101
	v_fmac_f32_e32 v112, v102, v102
	v_fmac_f32_e32 v112, v103, v103
	v_mov_b32_e32 v116, v112
	s_nop 1
;     template <int TYPE  >
;     __device__ __forceinline__ void rows(const pg8::f32x4 (&acc)[2][2][4][2], const pg8::Unit& u, int wr, int fr, int fq, const float (&rstd)[2][4], bf16_t* dst, int ld, const float* gain, float qs) const {
;     ...
;                 const int row = u.pm * 256 + ai * 128 + wr * 64 + m * 16 + fr;
;                 float v[2][2][4];
;                 if (TYPE == 0) {
;                     float ss = 0.f;
; #pragma unroll
;                     for (int bj = 0; bj < 2; ++bj)
; #pragma unroll
;                         for (int n = 0; n < 2; ++n)
; #pragma unroll
;                             for (int e = 0; e < 4; ++e) ss += acc[ai][bj][m][n][e] * acc[ai][bj][m][n][e];
;                     ss = sum_fq(ss);
;                     const float r1 = rstd[ai][m], sc = r1 * __builtin_amdgcn_rsqf(r1 * r1 * ss * (1.0f / 64.0f) + EPS);
; #pragma unroll
;                     for (int bj = 0; bj < 2; ++bj)
; #pragma unroll
;                         for (int n = 0; n < 2; ++n)
; #pragma unroll
;                             for (int e = 0; e < 4; ++e) v[bj][n][e] = acc[ai][bj][m][n][e] * sc * gn[bj][n][e];
;                     const float* rp = rope + (size_t)(row & (SEQ - 1)) * 16 + 4 * (fq & 1);
;                     const f32x4 cs = *(const f32x4*)rp, sn = *(const f32x4*)(rp + 8);
; #pragma unroll
;                     for (int e = 0; e < 4; ++e) {
;                         const float t1 = v[0][0][e], t2 = v[0][1][e];
;                         const float o1 = t1 * cs[e] - t2 * sn[e], o2 = t2 * cs[e] + t1 * sn[e];
;                         v[0][0][e] = fq < 2 ? o1 : t1; v[0][1][e] = fq < 2 ? o2 : t2;
;                     }
;                 } else {
; #pragma unroll
;                     for (int bj = 0; bj < 2; ++bj)
; #pragma unroll
;                         for (int n = 0; n < 2; ++n)
; #pragma unroll
;                             for (int e = 0; e < 4; ++e) { const float z = acc[ai][bj][m][n][e] * rstd[ai][m]; v[bj][n][e] = TYPE == 3 ? z * __builtin_amdgcn_rcpf(1.0f + __expf(-z)) : z; }
;                 }
;                 bf16_t* rowp = dst + (size_t)row * ld;
; #pragma unroll
;                 for (int bj = 0; bj < 2; ++bj) {
;                     u32x4 w; w.x = pkbf(v[bj][0][0], v[bj][0][1]); w.y = pkbf(v[bj][0][2], v[bj][0][3]); w.z = pkbf(v[bj][1][0], v[bj][1][1]); w.w = pkbf(v[bj][1][2], v[bj][1][3]);
	v_permlane16_swap_b32_e32 v112, v116
	v_add_f32_e32 v112, v112, v116
	v_mov_b32_e32 v116, v112
	s_nop 1
	v_permlane32_swap_b32_e32 v112, v116
	v_add_f32_e32 v112, v112, v116
	v_mul_f32_e32 v116, v184, v184
	v_mul_f32_e32 v112, v116, v112
	v_fmamk_f32 v112, v112, 0x3c800000, v198
	v_rsq_f32_e32 v112, v112
	s_nop 0
	v_mul_lo_u32 v120, s26, v206
	v_mul_f32_e32 v116, v184, v112
	v_ashrrev_i32_e32 v112, 31, v206
	s_nop 0
	v_mov_b32_e64 v121, 0
	v_add_u32_e32 v117, s19, v177
	v_pk_mul_f32 v[108:109], v[108:109], v[116:117] op_sel_hi:[1,0]
	v_pk_mul_f32 v[110:111], v[110:111], v[116:117] op_sel_hi:[1,0]
	v_pk_mul_f32 v[100:101], v[100:101], v[116:117] op_sel_hi:[1,0]
	v_pk_mul_f32 v[108:109], v[128:129], v[108:109]
	v_pk_mul_f32 v[110:111], v[126:127], v[110:111]
	v_pk_mul_f32 v[100:101], v[124:125], v[100:101]
	v_cvt_pk_bf16_f32 v108, v108, v109
	v_cvt_pk_bf16_f32 v109, v110, v111
	v_cvt_pk_bf16_f32 v110, v100, v101
	v_pk_mul_f32 v[100:101], v[102:103], v[116:117] op_sel_hi:[1,0]
	v_pk_mul_f32 v[96:97], v[96:97], v[116:117] op_sel_hi:[1,0]
	v_pk_mul_f32 v[100:101], v[122:123], v[100:101]
	v_pk_mul_f32 v[96:97], v[114:115], v[96:97]
	v_cvt_pk_bf16_f32 v111, v100, v101
	v_pk_mul_f32 v[100:101], v[104:105], v[116:117] op_sel_hi:[1,0]
	v_mov_b32_e32 v105, v96
	v_pk_mul_f32 v[100:101], v[118:119], v[100:101]
	v_lshlrev_b32_e32 v112, 6, v117
	v_mov_b32_e32 v104, v100
	v_and_b32_e32 v112, 0x3fbc0, v112
	v_lshl_add_u64 v[142:143], v[164:165], 0, v[112:113]
	v_pk_mul_f32 v[98:99], v[98:99], v[116:117] op_sel_hi:[1,0]
	v_lshl_add_u64 v[120:121], v[120:121], 1, v[170:171]
	v_pk_mul_f32 v[98:99], v[132:133], v[98:99]
	v_add_u32_e32 v148, s19, v191
	s_waitcnt vmcnt(1)
	v_mov_b32_e32 v102, v134
	s_waitcnt vmcnt(0)
	v_mov_b32_e32 v103, v138
	v_pk_mul_f32 v[102:103], v[102:103], v[104:105]
	v_mov_b32_e32 v104, v101
	v_sub_f32_e32 v102, v102, v103
	v_cndmask_b32_e64 v112, v100, v102, s[38:39]
	v_mov_b32_e32 v102, v135
	v_mov_b32_e32 v103, v139
	v_mov_b32_e32 v105, v97
	v_pk_mul_f32 v[102:103], v[102:103], v[104:105]
	s_nop 0
	v_sub_f32_e32 v104, v102, v103
	v_pk_mul_f32 v[102:103], v[134:135], v[96:97]
	v_cndmask_b32_e64 v104, v101, v104, s[38:39]
	v_pk_fma_f32 v[102:103], v[138:139], v[100:101], v[102:103]
	v_mov_b32_e32 v100, v136
	v_cndmask_b32_e64 v105, v97, v103, s[38:39]
	v_cndmask_b32_e64 v134, v96, v102, s[38:39]
	v_pk_mul_f32 v[96:97], v[106:107], v[116:117] op_sel_hi:[1,0]
	v_mov_b32_e32 v101, v140
	v_pk_mul_f32 v[96:97], v[130:131], v[96:97]
	v_mov_b32_e32 v103, v98
	v_mov_b32_e32 v102, v96
	v_pk_mul_f32 v[100:101], v[100:101], v[102:103]
	v_mov_b32_e32 v102, v97
	v_sub_f32_e32 v100, v100, v101
	v_cndmask_b32_e64 v106, v96, v100, s[38:39]
	v_mov_b32_e32 v100, v137
	v_mov_b32_e32 v101, v141
	v_mov_b32_e32 v103, v99
	v_pk_mul_f32 v[100:101], v[100:101], v[102:103]
	s_nop 0
	v_sub_f32_e32 v102, v100, v101
	v_pk_mul_f32 v[100:101], v[136:137], v[98:99]
	s_nop 0
	v_pk_fma_f32 v[100:101], v[140:141], v[96:97], v[100:101]
	v_cndmask_b32_e64 v97, v97, v102, s[38:39]
	v_cndmask_b32_e64 v99, v99, v101, s[38:39]
	v_cndmask_b32_e64 v100, v98, v100, s[38:39]
	v_cvt_pk_bf16_f32 v96, v112, v104
	v_cvt_pk_bf16_f32 v97, v106, v97
	v_cvt_pk_bf16_f32 v98, v134, v105
	v_cvt_pk_bf16_f32 v99, v100, v99
	global_store_dwordx4 v[120:121], v[96:99], off
	global_store_dwordx4 v[120:121], v[108:111], off offset:64
	global_load_dwordx4 v[96:99], v[142:143], off
	s_nop 0
	global_load_dwordx4 v[100:103], v[142:143], off offset:32
	v_mul_f32_e32 v104, v89, v89
	v_fmac_f32_e32 v104, v88, v88
	v_fmac_f32_e32 v104, v90, v90
	v_fmac_f32_e32 v104, v91, v91
	v_fmac_f32_e32 v104, v80, v80
	v_fmac_f32_e32 v104, v81, v81
	v_fmac_f32_e32 v104, v82, v82
	v_fmac_f32_e32 v104, v83, v83
	v_fmac_f32_e32 v104, v92, v92
	v_fmac_f32_e32 v104, v93, v93
	v_fmac_f32_e32 v104, v94, v94
	v_fmac_f32_e32 v104, v95, v95
	v_fmac_f32_e32 v104, v84, v84
	v_fmac_f32_e32 v104, v85, v85
	v_fmac_f32_e32 v104, v86, v86
	v_fmac_f32_e32 v104, v87, v87
	v_mov_b32_e32 v105, v104
	s_nop 1
	v_permlane16_swap_b32_e32 v104, v105
	v_add_f32_e32 v104, v104, v105
	v_mov_b32_e32 v105, v104
	s_nop 1
	v_permlane32_swap_b32_e32 v104, v105
	v_add_f32_e32 v104, v104, v105
	v_mul_f32_e32 v105, v182, v182
	v_mul_f32_e32 v104, v105, v104
	v_fmamk_f32 v104, v104, 0x3c800000, v198
	v_rsq_f32_e32 v104, v104
	v_ashrrev_i32_e32 v105, 31, v117
	s_nop 0
	s_nop 0
	v_mul_lo_u32 v106, s26, v117
	v_mul_f32_e32 v104, v182, v104
	v_mov_b32_e64 v107, 0
	v_add_u32_e32 v105, s19, v179
	v_pk_mul_f32 v[92:93], v[92:93], v[104:105] op_sel_hi:[1,0]
	v_pk_mul_f32 v[94:95], v[94:95], v[104:105] op_sel_hi:[1,0]
	v_pk_mul_f32 v[84:85], v[84:85], v[104:105] op_sel_hi:[1,0]
	v_pk_mul_f32 v[92:93], v[128:129], v[92:93]
	v_pk_mul_f32 v[94:95], v[126:127], v[94:95]
	v_pk_mul_f32 v[84:85], v[124:125], v[84:85]
	v_cvt_pk_bf16_f32 v92, v92, v93
	v_cvt_pk_bf16_f32 v93, v94, v95
	v_cvt_pk_bf16_f32 v94, v84, v85
	v_pk_mul_f32 v[84:85], v[86:87], v[104:105] op_sel_hi:[1,0]
	v_pk_mul_f32 v[80:81], v[80:81], v[104:105] op_sel_hi:[1,0]
	v_pk_mul_f32 v[84:85], v[122:123], v[84:85]
	v_pk_mul_f32 v[80:81], v[114:115], v[80:81]
	v_cvt_pk_bf16_f32 v95, v84, v85
	v_pk_mul_f32 v[84:85], v[88:89], v[104:105] op_sel_hi:[1,0]
	v_mov_b32_e32 v89, v80
	v_pk_mul_f32 v[84:85], v[118:119], v[84:85]
	v_pk_mul_f32 v[82:83], v[82:83], v[104:105] op_sel_hi:[1,0]
	v_mov_b32_e32 v88, v84
	v_pk_mul_f32 v[82:83], v[132:133], v[82:83]
	v_lshlrev_b32_e32 v108, 6, v105
	v_lshl_add_u64 v[106:107], v[106:107], 1, v[170:171]
	v_and_b32_e32 v112, 0x3ffc0, v108
	v_lshl_add_u64 v[108:109], v[164:165], 0, v[112:113]
	s_waitcnt vmcnt(1)
	v_mov_b32_e32 v86, v96
	s_waitcnt vmcnt(0)
;     template <int TYPE  >
;     __device__ __forceinline__ void rows(const pg8::f32x4 (&acc)[2][2][4][2], const pg8::Unit& u, int wr, int fr, int fq, const float (&rstd)[2][4], bf16_t* dst, int ld, const float* gain, float qs) const {
;     ...
;                 const int row = u.pm * 256 + ai * 128 + wr * 64 + m * 16 + fr;
;                 float v[2][2][4];
;                 if (TYPE == 0) {
;                     float ss = 0.f;
; #pragma unroll
;                     for (int bj = 0; bj < 2; ++bj)
; #pragma unroll
;                         for (int n = 0; n < 2; ++n)
; #pragma unroll
;                             for (int e = 0; e < 4; ++e) ss += acc[ai][bj][m][n][e] * acc[ai][bj][m][n][e];
;                     ss = sum_fq(ss);
;                     const float r1 = rstd[ai][m], sc = r1 * __builtin_amdgcn_rsqf(r1 * r1 * ss * (1.0f / 64.0f) + EPS);
; #pragma unroll
;                     for (int bj = 0; bj < 2; ++bj)
; #pragma unroll
;                         for (int n = 0; n < 2; ++n)
; #pragma unroll
;                             for (int e = 0; e < 4; ++e) v[bj][n][e] = acc[ai][bj][m][n][e] * sc * gn[bj][n][e];
;                     const float* rp = rope + (size_t)(row & (SEQ - 1)) * 16 + 4 * (fq & 1);
;                     const f32x4 cs = *(const f32x4*)rp, sn = *(const f32x4*)(rp + 8);
; #pragma unroll
;                     for (int e = 0; e < 4; ++e) {
;                         const float t1 = v[0][0][e], t2 = v[0][1][e];
;                         const float o1 = t1 * cs[e] - t2 * sn[e], o2 = t2 * cs[e] + t1 * sn[e];
;                         v[0][0][e] = fq < 2 ? o1 : t1; v[0][1][e] = fq < 2 ? o2 : t2;
;                     }
;                 } else {
; #pragma unroll
;                     for (int bj = 0; bj < 2; ++bj)
; #pragma unroll
;                         for (int n = 0; n < 2; ++n)
; #pragma unroll
;                             for (int e = 0; e < 4; ++e) { const float z = acc[ai][bj][m][n][e] * rstd[ai][m]; v[bj][n][e] = TYPE == 3 ? z * __builtin_amdgcn_rcpf(1.0f + __expf(-z)) : z; }
;                 }
;                 bf16_t* rowp = dst + (size_t)row * ld;
; #pragma unroll
;                 for (int bj = 0; bj < 2; ++bj) {
;                     u32x4 w; w.x = pkbf(v[bj][0][0], v[bj][0][1]); w.y = pkbf(v[bj][0][2], v[bj][0][3]); w.z = pkbf(v[bj][1][0], v[bj][1][1]); w.w = pkbf(v[bj][1][2], v[bj][1][3]);
	v_mov_b32_e32 v87, v100
	v_pk_mul_f32 v[86:87], v[86:87], v[88:89]
	v_mov_b32_e32 v88, v85
	v_sub_f32_e32 v86, v86, v87
	v_cndmask_b32_e64 v110, v84, v86, s[38:39]
	v_mov_b32_e32 v86, v97
	v_mov_b32_e32 v87, v101
	v_mov_b32_e32 v89, v81
	v_pk_mul_f32 v[86:87], v[86:87], v[88:89]
	s_nop 0
	v_sub_f32_e32 v88, v86, v87
	v_pk_mul_f32 v[86:87], v[96:97], v[80:81]
	v_cndmask_b32_e64 v88, v85, v88, s[38:39]
	v_pk_fma_f32 v[86:87], v[100:101], v[84:85], v[86:87]
	v_mov_b32_e32 v84, v98
	v_cndmask_b32_e64 v89, v81, v87, s[38:39]
	v_cndmask_b32_e64 v96, v80, v86, s[38:39]
	v_pk_mul_f32 v[80:81], v[90:91], v[104:105] op_sel_hi:[1,0]
	v_mov_b32_e32 v85, v102
	v_pk_mul_f32 v[80:81], v[130:131], v[80:81]
	v_mov_b32_e32 v87, v82
	v_mov_b32_e32 v86, v80
	v_pk_mul_f32 v[84:85], v[84:85], v[86:87]
	v_mov_b32_e32 v86, v81
	v_sub_f32_e32 v84, v84, v85
	v_cndmask_b32_e64 v90, v80, v84, s[38:39]
	v_mov_b32_e32 v84, v99
	v_mov_b32_e32 v85, v103
	v_mov_b32_e32 v87, v83
	v_pk_mul_f32 v[84:85], v[84:85], v[86:87]
	s_nop 0
	v_sub_f32_e32 v86, v84, v85
	v_pk_mul_f32 v[84:85], v[98:99], v[82:83]
	s_nop 0
	v_pk_fma_f32 v[84:85], v[102:103], v[80:81], v[84:85]
	v_cndmask_b32_e64 v81, v81, v86, s[38:39]
	v_cndmask_b32_e64 v83, v83, v85, s[38:39]
	v_cndmask_b32_e64 v84, v82, v84, s[38:39]
	v_cvt_pk_bf16_f32 v80, v110, v88
	v_cvt_pk_bf16_f32 v81, v90, v81
	v_cvt_pk_bf16_f32 v82, v96, v89
	v_cvt_pk_bf16_f32 v83, v84, v83
	global_store_dwordx4 v[106:107], v[80:83], off
	global_store_dwordx4 v[106:107], v[92:95], off offset:64
	global_load_dwordx4 v[80:83], v[108:109], off
	s_nop 0
	global_load_dwordx4 v[84:87], v[108:109], off offset:32
	v_mul_f32_e32 v88, v73, v73
	v_fmac_f32_e32 v88, v72, v72
	v_fmac_f32_e32 v88, v74, v74
	v_fmac_f32_e32 v88, v75, v75
	v_fmac_f32_e32 v88, v64, v64
	v_fmac_f32_e32 v88, v65, v65
	v_fmac_f32_e32 v88, v66, v66
	v_fmac_f32_e32 v88, v67, v67
	v_fmac_f32_e32 v88, v76, v76
	v_fmac_f32_e32 v88, v77, v77
	v_fmac_f32_e32 v88, v78, v78
	v_fmac_f32_e32 v88, v79, v79
	v_fmac_f32_e32 v88, v68, v68
	v_fmac_f32_e32 v88, v69, v69
	v_fmac_f32_e32 v88, v70, v70
	v_fmac_f32_e32 v88, v71, v71
	v_mov_b32_e32 v89, v88
	s_nop 1
	v_permlane16_swap_b32_e32 v88, v89
	v_add_f32_e32 v88, v88, v89
	v_mov_b32_e32 v89, v88
	s_nop 1
	v_permlane32_swap_b32_e32 v88, v89
	v_add_f32_e32 v88, v88, v89
	v_mul_f32_e32 v89, v180, v180
	v_mul_f32_e32 v88, v89, v88
	v_fmamk_f32 v88, v88, 0x3c800000, v198
	v_rsq_f32_e32 v88, v88
	v_ashrrev_i32_e32 v89, 31, v105
	s_nop 0
	s_nop 0
	v_mul_lo_u32 v90, s26, v105
	v_mul_f32_e32 v88, v180, v88
	v_mov_b32_e64 v91, 0
	v_add_u32_e32 v89, s19, v181
	v_pk_mul_f32 v[76:77], v[76:77], v[88:89] op_sel_hi:[1,0]
	v_pk_mul_f32 v[78:79], v[78:79], v[88:89] op_sel_hi:[1,0]
	v_pk_mul_f32 v[68:69], v[68:69], v[88:89] op_sel_hi:[1,0]
	v_pk_mul_f32 v[76:77], v[128:129], v[76:77]
	v_pk_mul_f32 v[78:79], v[126:127], v[78:79]
	v_pk_mul_f32 v[68:69], v[124:125], v[68:69]
	v_cvt_pk_bf16_f32 v76, v76, v77
	v_cvt_pk_bf16_f32 v77, v78, v79
	v_cvt_pk_bf16_f32 v78, v68, v69
	v_pk_mul_f32 v[68:69], v[70:71], v[88:89] op_sel_hi:[1,0]
	v_pk_mul_f32 v[64:65], v[64:65], v[88:89] op_sel_hi:[1,0]
	v_pk_mul_f32 v[68:69], v[122:123], v[68:69]
	v_pk_mul_f32 v[64:65], v[114:115], v[64:65]
	v_cvt_pk_bf16_f32 v79, v68, v69
	v_pk_mul_f32 v[68:69], v[72:73], v[88:89] op_sel_hi:[1,0]
	v_mov_b32_e32 v73, v64
	v_pk_mul_f32 v[68:69], v[118:119], v[68:69]
	v_pk_mul_f32 v[66:67], v[66:67], v[88:89] op_sel_hi:[1,0]
	v_mov_b32_e32 v72, v68
	v_pk_mul_f32 v[66:67], v[132:133], v[66:67]
	v_lshlrev_b32_e32 v92, 6, v89
	v_lshl_add_u64 v[90:91], v[90:91], 1, v[170:171]
	v_and_b32_e32 v112, 0x3f3c0, v92
	v_lshl_add_u64 v[92:93], v[164:165], 0, v[112:113]
	s_waitcnt vmcnt(1)
	v_mov_b32_e32 v70, v80
	s_waitcnt vmcnt(0)
	v_mov_b32_e32 v71, v84
	v_pk_mul_f32 v[70:71], v[70:71], v[72:73]
	v_mov_b32_e32 v72, v69
	v_sub_f32_e32 v70, v70, v71
	v_cndmask_b32_e64 v94, v68, v70, s[38:39]
	v_mov_b32_e32 v70, v81
	v_mov_b32_e32 v71, v85
	v_mov_b32_e32 v73, v65
	v_pk_mul_f32 v[70:71], v[70:71], v[72:73]
	s_nop 0
	v_sub_f32_e32 v72, v70, v71
	v_pk_mul_f32 v[70:71], v[80:81], v[64:65]
	v_cndmask_b32_e64 v72, v69, v72, s[38:39]
	v_pk_fma_f32 v[70:71], v[84:85], v[68:69], v[70:71]
	v_mov_b32_e32 v68, v82
	v_cndmask_b32_e64 v73, v65, v71, s[38:39]
	v_cndmask_b32_e64 v80, v64, v70, s[38:39]
	v_pk_mul_f32 v[64:65], v[74:75], v[88:89] op_sel_hi:[1,0]
	v_mov_b32_e32 v69, v86
	v_pk_mul_f32 v[64:65], v[130:131], v[64:65]
	v_mov_b32_e32 v71, v66
	v_mov_b32_e32 v70, v64
	v_pk_mul_f32 v[68:69], v[68:69], v[70:71]
	v_mov_b32_e32 v70, v65
	v_sub_f32_e32 v68, v68, v69
	v_cndmask_b32_e64 v74, v64, v68, s[38:39]
	v_mov_b32_e32 v68, v83
	v_mov_b32_e32 v69, v87
	v_mov_b32_e32 v71, v67
	v_pk_mul_f32 v[68:69], v[68:69], v[70:71]
	s_nop 0
	v_sub_f32_e32 v70, v68, v69
	v_pk_mul_f32 v[68:69], v[82:83], v[66:67]
	s_nop 0
	v_pk_fma_f32 v[68:69], v[86:87], v[64:65], v[68:69]
	v_cndmask_b32_e64 v65, v65, v70, s[38:39]
	v_cndmask_b32_e64 v67, v67, v69, s[38:39]
	v_cndmask_b32_e64 v68, v66, v68, s[38:39]
	v_cvt_pk_bf16_f32 v64, v94, v72
	v_cvt_pk_bf16_f32 v65, v74, v65
	v_cvt_pk_bf16_f32 v66, v80, v73
	v_cvt_pk_bf16_f32 v67, v68, v67
	global_store_dwordx4 v[90:91], v[64:67], off
	global_store_dwordx4 v[90:91], v[76:79], off offset:64
	global_load_dwordx4 v[64:67], v[92:93], off
	s_nop 0
	global_load_dwordx4 v[68:71], v[92:93], off offset:32
	v_mul_f32_e32 v72, v57, v57
	v_fmac_f32_e32 v72, v56, v56
	v_fmac_f32_e32 v72, v58, v58
	v_fmac_f32_e32 v72, v59, v59
	v_fmac_f32_e32 v72, v48, v48
	v_fmac_f32_e32 v72, v49, v49
	v_fmac_f32_e32 v72, v50, v50
	v_fmac_f32_e32 v72, v51, v51
	v_fmac_f32_e32 v72, v60, v60
	v_fmac_f32_e32 v72, v61, v61
;     template <int TYPE  >
;     __device__ __forceinline__ void rows(const pg8::f32x4 (&acc)[2][2][4][2], const pg8::Unit& u, int wr, int fr, int fq, const float (&rstd)[2][4], bf16_t* dst, int ld, const float* gain, float qs) const {
;     ...
;                     float ss = 0.f;
; #pragma unroll
;                     for (int bj = 0; bj < 2; ++bj)
; #pragma unroll
;                         for (int n = 0; n < 2; ++n)
; #pragma unroll
;                             for (int e = 0; e < 4; ++e) ss += acc[ai][bj][m][n][e] * acc[ai][bj][m][n][e];
;                     ss = sum_fq(ss);
;                     const float r1 = rstd[ai][m], sc = r1 * __builtin_amdgcn_rsqf(r1 * r1 * ss * (1.0f / 64.0f) + EPS);
; #pragma unroll
;                     for (int bj = 0; bj < 2; ++bj)
; #pragma unroll
;                         for (int n = 0; n < 2; ++n)
; #pragma unroll
;                             for (int e = 0; e < 4; ++e) v[bj][n][e] = acc[ai][bj][m][n][e] * sc * gn[bj][n][e];
;                     const float* rp = rope + (size_t)(row & (SEQ - 1)) * 16 + 4 * (fq & 1);
;                     const f32x4 cs = *(const f32x4*)rp, sn = *(const f32x4*)(rp + 8);
; #pragma unroll
;                     for (int e = 0; e < 4; ++e) {
;                         const float t1 = v[0][0][e], t2 = v[0][1][e];
;                         const float o1 = t1 * cs[e] - t2 * sn[e], o2 = t2 * cs[e] + t1 * sn[e];
;                         v[0][0][e] = fq < 2 ? o1 : t1; v[0][1][e] = fq < 2 ? o2 : t2;
;                     }
;                 } else {
; #pragma unroll
;                     for (int bj = 0; bj < 2; ++bj)
; #pragma unroll
;                         for (int n = 0; n < 2; ++n)
; #pragma unroll
;                             for (int e = 0; e < 4; ++e) { const float z = acc[ai][bj][m][n][e] * rstd[ai][m]; v[bj][n][e] = TYPE == 3 ? z * __builtin_amdgcn_rcpf(1.0f + __expf(-z)) : z; }
;                 }
;                 bf16_t* rowp = dst + (size_t)row * ld;
; #pragma unroll
;                 for (int bj = 0; bj < 2; ++bj) {
;                     u32x4 w; w.x = pkbf(v[bj][0][0], v[bj][0][1]); w.y = pkbf(v[bj][0][2], v[bj][0][3]); w.z = pkbf(v[bj][1][0], v[bj][1][1]); w.w = pkbf(v[bj][1][2], v[bj][1][3]);
;                     *(u32x4*)(rowp + 32 * bj) = w;
	v_fmac_f32_e32 v72, v62, v62
	v_fmac_f32_e32 v72, v63, v63
	v_fmac_f32_e32 v72, v52, v52
	v_fmac_f32_e32 v72, v53, v53
	v_fmac_f32_e32 v72, v54, v54
	v_fmac_f32_e32 v72, v55, v55
	v_mov_b32_e32 v73, v72
	s_nop 1
	v_permlane16_swap_b32_e32 v72, v73
	v_add_f32_e32 v72, v72, v73
	v_mov_b32_e32 v73, v72
	s_nop 1
	v_permlane32_swap_b32_e32 v72, v73
	v_add_f32_e32 v72, v72, v73
	v_mul_f32_e32 v73, v178, v178
	v_mul_f32_e32 v72, v73, v72
	v_fmamk_f32 v72, v72, 0x3c800000, v198
	v_rsq_f32_e32 v72, v72
	v_ashrrev_i32_e32 v73, 31, v89
	s_nop 0
	s_nop 0
	v_mul_lo_u32 v74, s26, v89
	v_mul_f32_e32 v72, v178, v72
	v_mov_b32_e64 v75, 0
	v_add_u32_e32 v73, s19, v183
	v_pk_mul_f32 v[60:61], v[60:61], v[72:73] op_sel_hi:[1,0]
	v_pk_mul_f32 v[62:63], v[62:63], v[72:73] op_sel_hi:[1,0]
	v_pk_mul_f32 v[52:53], v[52:53], v[72:73] op_sel_hi:[1,0]
	v_pk_mul_f32 v[60:61], v[128:129], v[60:61]
	v_pk_mul_f32 v[62:63], v[126:127], v[62:63]
	v_pk_mul_f32 v[52:53], v[124:125], v[52:53]
	v_cvt_pk_bf16_f32 v60, v60, v61
	v_cvt_pk_bf16_f32 v61, v62, v63
	v_cvt_pk_bf16_f32 v62, v52, v53
	v_pk_mul_f32 v[52:53], v[54:55], v[72:73] op_sel_hi:[1,0]
	v_pk_mul_f32 v[48:49], v[48:49], v[72:73] op_sel_hi:[1,0]
	v_pk_mul_f32 v[52:53], v[122:123], v[52:53]
	v_pk_mul_f32 v[48:49], v[114:115], v[48:49]
	v_cvt_pk_bf16_f32 v63, v52, v53
	v_pk_mul_f32 v[52:53], v[56:57], v[72:73] op_sel_hi:[1,0]
	v_mov_b32_e32 v57, v48
	v_pk_mul_f32 v[52:53], v[118:119], v[52:53]
	v_pk_mul_f32 v[50:51], v[50:51], v[72:73] op_sel_hi:[1,0]
	v_mov_b32_e32 v56, v52
	v_pk_mul_f32 v[50:51], v[132:133], v[50:51]
	v_lshlrev_b32_e32 v76, 6, v73
	v_lshl_add_u64 v[74:75], v[74:75], 1, v[170:171]
	v_and_b32_e32 v112, 0x3f7c0, v76
	v_lshl_add_u64 v[76:77], v[164:165], 0, v[112:113]
	s_waitcnt vmcnt(1)
	v_mov_b32_e32 v54, v64
	s_waitcnt vmcnt(0)
	v_mov_b32_e32 v55, v68
	v_pk_mul_f32 v[54:55], v[54:55], v[56:57]
	v_mov_b32_e32 v56, v53
	v_sub_f32_e32 v54, v54, v55
	v_cndmask_b32_e64 v78, v52, v54, s[38:39]
	v_mov_b32_e32 v54, v65
	v_mov_b32_e32 v55, v69
	v_mov_b32_e32 v57, v49
	v_pk_mul_f32 v[54:55], v[54:55], v[56:57]
	s_nop 0
	v_sub_f32_e32 v56, v54, v55
	v_pk_mul_f32 v[54:55], v[64:65], v[48:49]
	v_cndmask_b32_e64 v56, v53, v56, s[38:39]
	v_pk_fma_f32 v[54:55], v[68:69], v[52:53], v[54:55]
	v_mov_b32_e32 v52, v66
	v_cndmask_b32_e64 v57, v49, v55, s[38:39]
	v_cndmask_b32_e64 v64, v48, v54, s[38:39]
	v_pk_mul_f32 v[48:49], v[58:59], v[72:73] op_sel_hi:[1,0]
	v_mov_b32_e32 v53, v70
	v_pk_mul_f32 v[48:49], v[130:131], v[48:49]
	v_mov_b32_e32 v55, v50
	v_mov_b32_e32 v54, v48
	v_pk_mul_f32 v[52:53], v[52:53], v[54:55]
	v_mov_b32_e32 v54, v49
	v_sub_f32_e32 v52, v52, v53
	v_cndmask_b32_e64 v58, v48, v52, s[38:39]
	v_mov_b32_e32 v52, v67
	v_mov_b32_e32 v53, v71
	v_mov_b32_e32 v55, v51
	v_pk_mul_f32 v[52:53], v[52:53], v[54:55]
	s_nop 0
	v_sub_f32_e32 v54, v52, v53
	v_pk_mul_f32 v[52:53], v[66:67], v[50:51]
	s_nop 0
	v_pk_fma_f32 v[52:53], v[70:71], v[48:49], v[52:53]
	v_cndmask_b32_e64 v49, v49, v54, s[38:39]
	v_cndmask_b32_e64 v51, v51, v53, s[38:39]
	v_cndmask_b32_e64 v52, v50, v52, s[38:39]
	v_cvt_pk_bf16_f32 v48, v78, v56
	v_cvt_pk_bf16_f32 v49, v58, v49
	v_cvt_pk_bf16_f32 v50, v64, v57
	v_cvt_pk_bf16_f32 v51, v52, v51
	global_store_dwordx4 v[74:75], v[48:51], off
	global_store_dwordx4 v[74:75], v[60:63], off offset:64
	global_load_dwordx4 v[48:51], v[76:77], off
	s_nop 0
	global_load_dwordx4 v[52:55], v[76:77], off offset:32
	v_mul_f32_e32 v56, v41, v41
	v_fmac_f32_e32 v56, v40, v40
	v_fmac_f32_e32 v56, v42, v42
	v_fmac_f32_e32 v56, v43, v43
	v_fmac_f32_e32 v56, v32, v32
	v_fmac_f32_e32 v56, v33, v33
	v_fmac_f32_e32 v56, v34, v34
	v_fmac_f32_e32 v56, v35, v35
	v_fmac_f32_e32 v56, v44, v44
	v_fmac_f32_e32 v56, v45, v45
	v_fmac_f32_e32 v56, v46, v46
	v_fmac_f32_e32 v56, v47, v47
	v_fmac_f32_e32 v56, v36, v36
	v_fmac_f32_e32 v56, v37, v37
	v_fmac_f32_e32 v56, v38, v38
	v_fmac_f32_e32 v56, v39, v39
	v_mov_b32_e32 v57, v56
	s_nop 1
	v_permlane16_swap_b32_e32 v56, v57
	v_add_f32_e32 v56, v56, v57
	v_mov_b32_e32 v57, v56
	s_nop 1
	v_permlane32_swap_b32_e32 v56, v57
	v_add_f32_e32 v56, v56, v57
	v_mul_f32_e32 v57, v176, v176
	v_mul_f32_e32 v56, v57, v56
	v_fmamk_f32 v56, v56, 0x3c800000, v198
	v_rsq_f32_e32 v56, v56
	v_ashrrev_i32_e32 v57, 31, v73
	s_nop 0
	s_nop 0
	v_mul_lo_u32 v58, s26, v73
	v_mul_f32_e32 v56, v176, v56
	v_mov_b32_e64 v59, 0
	v_add_u32_e32 v57, s19, v185
	v_pk_mul_f32 v[44:45], v[44:45], v[56:57] op_sel_hi:[1,0]
	v_pk_mul_f32 v[46:47], v[46:47], v[56:57] op_sel_hi:[1,0]
	v_pk_mul_f32 v[36:37], v[36:37], v[56:57] op_sel_hi:[1,0]
	v_pk_mul_f32 v[44:45], v[128:129], v[44:45]
	v_pk_mul_f32 v[46:47], v[126:127], v[46:47]
	v_pk_mul_f32 v[36:37], v[124:125], v[36:37]
	v_cvt_pk_bf16_f32 v44, v44, v45
	v_cvt_pk_bf16_f32 v45, v46, v47
	v_cvt_pk_bf16_f32 v46, v36, v37
	v_pk_mul_f32 v[36:37], v[38:39], v[56:57] op_sel_hi:[1,0]
	v_pk_mul_f32 v[32:33], v[32:33], v[56:57] op_sel_hi:[1,0]
	v_pk_mul_f32 v[36:37], v[122:123], v[36:37]
	v_pk_mul_f32 v[32:33], v[114:115], v[32:33]
	v_cvt_pk_bf16_f32 v47, v36, v37
	v_pk_mul_f32 v[36:37], v[40:41], v[56:57] op_sel_hi:[1,0]
	v_mov_b32_e32 v41, v32
	v_pk_mul_f32 v[36:37], v[118:119], v[36:37]
	v_pk_mul_f32 v[34:35], v[34:35], v[56:57] op_sel_hi:[1,0]
	v_mov_b32_e32 v40, v36
	v_pk_mul_f32 v[34:35], v[132:133], v[34:35]
	v_lshlrev_b32_e32 v60, 6, v57
	v_lshl_add_u64 v[58:59], v[58:59], 1, v[170:171]
	v_and_b32_e32 v112, 0x3fbc0, v60
	v_lshl_add_u64 v[60:61], v[164:165], 0, v[112:113]
	s_waitcnt vmcnt(1)
	v_mov_b32_e32 v38, v48
	s_waitcnt vmcnt(0)
;     template <int TYPE  >
;     __device__ __forceinline__ void rows(const pg8::f32x4 (&acc)[2][2][4][2], const pg8::Unit& u, int wr, int fr, int fq, const float (&rstd)[2][4], bf16_t* dst, int ld, const float* gain, float qs) const {
;     ...
;                     float ss = 0.f;
; #pragma unroll
;                     for (int bj = 0; bj < 2; ++bj)
; #pragma unroll
;                         for (int n = 0; n < 2; ++n)
; #pragma unroll
;                             for (int e = 0; e < 4; ++e) ss += acc[ai][bj][m][n][e] * acc[ai][bj][m][n][e];
;                     ss = sum_fq(ss);
;                     const float r1 = rstd[ai][m], sc = r1 * __builtin_amdgcn_rsqf(r1 * r1 * ss * (1.0f / 64.0f) + EPS);
; #pragma unroll
;                     for (int bj = 0; bj < 2; ++bj)
; #pragma unroll
;                         for (int n = 0; n < 2; ++n)
; #pragma unroll
;                             for (int e = 0; e < 4; ++e) v[bj][n][e] = acc[ai][bj][m][n][e] * sc * gn[bj][n][e];
;                     const float* rp = rope + (size_t)(row & (SEQ - 1)) * 16 + 4 * (fq & 1);
;                     const f32x4 cs = *(const f32x4*)rp, sn = *(const f32x4*)(rp + 8);
; #pragma unroll
;                     for (int e = 0; e < 4; ++e) {
;                         const float t1 = v[0][0][e], t2 = v[0][1][e];
;                         const float o1 = t1 * cs[e] - t2 * sn[e], o2 = t2 * cs[e] + t1 * sn[e];
;                         v[0][0][e] = fq < 2 ? o1 : t1; v[0][1][e] = fq < 2 ? o2 : t2;
;                     }
;                 } else {
; #pragma unroll
;                     for (int bj = 0; bj < 2; ++bj)
; #pragma unroll
;                         for (int n = 0; n < 2; ++n)
; #pragma unroll
;                             for (int e = 0; e < 4; ++e) { const float z = acc[ai][bj][m][n][e] * rstd[ai][m]; v[bj][n][e] = TYPE == 3 ? z * __builtin_amdgcn_rcpf(1.0f + __expf(-z)) : z; }
;                 }
;                 bf16_t* rowp = dst + (size_t)row * ld;
; #pragma unroll
;                 for (int bj = 0; bj < 2; ++bj) {
;                     u32x4 w; w.x = pkbf(v[bj][0][0], v[bj][0][1]); w.y = pkbf(v[bj][0][2], v[bj][0][3]); w.z = pkbf(v[bj][1][0], v[bj][1][1]); w.w = pkbf(v[bj][1][2], v[bj][1][3]);
;                     *(u32x4*)(rowp + 32 * bj) = w;
	v_mov_b32_e32 v39, v52
	v_pk_mul_f32 v[38:39], v[38:39], v[40:41]
	v_mov_b32_e32 v40, v37
	v_sub_f32_e32 v38, v38, v39
	v_cndmask_b32_e64 v62, v36, v38, s[38:39]
	v_mov_b32_e32 v38, v49
	v_mov_b32_e32 v39, v53
	v_mov_b32_e32 v41, v33
	v_pk_mul_f32 v[38:39], v[38:39], v[40:41]
	s_nop 0
	v_sub_f32_e32 v40, v38, v39
	v_pk_mul_f32 v[38:39], v[48:49], v[32:33]
	v_cndmask_b32_e64 v40, v37, v40, s[38:39]
	v_pk_fma_f32 v[38:39], v[52:53], v[36:37], v[38:39]
	v_mov_b32_e32 v36, v50
	v_cndmask_b32_e64 v41, v33, v39, s[38:39]
	v_cndmask_b32_e64 v48, v32, v38, s[38:39]
	v_pk_mul_f32 v[32:33], v[42:43], v[56:57] op_sel_hi:[1,0]
	v_mov_b32_e32 v37, v54
	v_pk_mul_f32 v[32:33], v[130:131], v[32:33]
	v_mov_b32_e32 v39, v34
	v_mov_b32_e32 v38, v32
	v_pk_mul_f32 v[36:37], v[36:37], v[38:39]
	v_mov_b32_e32 v38, v33
	v_sub_f32_e32 v36, v36, v37
	v_cndmask_b32_e64 v42, v32, v36, s[38:39]
	v_mov_b32_e32 v36, v51
	v_mov_b32_e32 v37, v55
	v_mov_b32_e32 v39, v35
	v_pk_mul_f32 v[36:37], v[36:37], v[38:39]
	s_nop 0
	v_sub_f32_e32 v38, v36, v37
	v_pk_mul_f32 v[36:37], v[50:51], v[34:35]
	s_nop 0
	v_pk_fma_f32 v[36:37], v[54:55], v[32:33], v[36:37]
	v_cndmask_b32_e64 v33, v33, v38, s[38:39]
	v_cndmask_b32_e64 v35, v35, v37, s[38:39]
	v_cndmask_b32_e64 v36, v34, v36, s[38:39]
	v_cvt_pk_bf16_f32 v32, v62, v40
	v_cvt_pk_bf16_f32 v33, v42, v33
	v_cvt_pk_bf16_f32 v34, v48, v41
	v_cvt_pk_bf16_f32 v35, v36, v35
	global_store_dwordx4 v[58:59], v[32:35], off
	global_store_dwordx4 v[58:59], v[44:47], off offset:64
	global_load_dwordx4 v[32:35], v[60:61], off
	s_nop 0
	global_load_dwordx4 v[36:39], v[60:61], off offset:32
	v_mul_f32_e32 v40, v25, v25
	v_fmac_f32_e32 v40, v24, v24
	v_fmac_f32_e32 v40, v26, v26
	v_fmac_f32_e32 v40, v27, v27
	v_fmac_f32_e32 v40, v16, v16
	v_fmac_f32_e32 v40, v17, v17
	v_fmac_f32_e32 v40, v18, v18
	v_fmac_f32_e32 v40, v19, v19
	v_fmac_f32_e32 v40, v28, v28
	v_fmac_f32_e32 v40, v29, v29
	v_fmac_f32_e32 v40, v30, v30
	v_fmac_f32_e32 v40, v31, v31
	v_fmac_f32_e32 v40, v20, v20
	v_fmac_f32_e32 v40, v21, v21
	v_fmac_f32_e32 v40, v22, v22
	v_fmac_f32_e32 v40, v23, v23
	v_mov_b32_e32 v41, v40
	s_nop 1
	v_permlane16_swap_b32_e32 v40, v41
	v_add_f32_e32 v40, v40, v41
	v_mov_b32_e32 v41, v40
	s_nop 1
	v_permlane32_swap_b32_e32 v40, v41
	v_add_f32_e32 v40, v40, v41
	v_mul_f32_e32 v41, v174, v174
	v_mul_f32_e32 v40, v41, v40
	v_fmamk_f32 v40, v40, 0x3c800000, v198
	v_rsq_f32_e32 v40, v40
	v_ashrrev_i32_e32 v41, 31, v57
	s_nop 0
	s_nop 0
	v_mul_f32_e32 v40, v174, v40
	v_pk_mul_f32 v[28:29], v[28:29], v[40:41] op_sel_hi:[1,0]
	v_pk_mul_f32 v[30:31], v[30:31], v[40:41] op_sel_hi:[1,0]
	v_pk_mul_f32 v[20:21], v[20:21], v[40:41] op_sel_hi:[1,0]
	v_pk_mul_f32 v[28:29], v[128:129], v[28:29]
	v_pk_mul_f32 v[30:31], v[126:127], v[30:31]
	v_pk_mul_f32 v[20:21], v[124:125], v[20:21]
	v_cvt_pk_bf16_f32 v28, v28, v29
	v_cvt_pk_bf16_f32 v29, v30, v31
	v_cvt_pk_bf16_f32 v30, v20, v21
	v_pk_mul_f32 v[20:21], v[22:23], v[40:41] op_sel_hi:[1,0]
	v_pk_mul_f32 v[22:23], v[24:25], v[40:41] op_sel_hi:[1,0]
	v_pk_mul_f32 v[16:17], v[16:17], v[40:41] op_sel_hi:[1,0]
	v_mul_lo_u32 v42, s26, v57
	v_pk_mul_f32 v[22:23], v[118:119], v[22:23]
	v_pk_mul_f32 v[16:17], v[114:115], v[16:17]
	v_mov_b32_e64 v43, 0
	v_mov_b32_e32 v44, v22
	v_mov_b32_e32 v45, v16
	v_pk_mul_f32 v[20:21], v[122:123], v[20:21]
	v_lshl_add_u64 v[42:43], v[42:43], 1, v[170:171]
	v_cvt_pk_bf16_f32 v31, v20, v21
	v_lshlrev_b32_e32 v20, 6, v148
	v_and_b32_e32 v112, 0x3ffc0, v20
	v_lshl_add_u64 v[20:21], v[164:165], 0, v[112:113]
	s_waitcnt vmcnt(1)
	v_mov_b32_e32 v24, v32
	s_waitcnt vmcnt(0)
;     template <int TYPE  >
;     __device__ __forceinline__ void rows(const pg8::f32x4 (&acc)[2][2][4][2], const pg8::Unit& u, int wr, int fr, int fq, const float (&rstd)[2][4], bf16_t* dst, int ld, const float* gain, float qs) const {
;     ...
;                     float ss = 0.f;
; #pragma unroll
;                     for (int bj = 0; bj < 2; ++bj)
; #pragma unroll
;                         for (int n = 0; n < 2; ++n)
; #pragma unroll
;                             for (int e = 0; e < 4; ++e) ss += acc[ai][bj][m][n][e] * acc[ai][bj][m][n][e];
;                     ss = sum_fq(ss);
;                     const float r1 = rstd[ai][m], sc = r1 * __builtin_amdgcn_rsqf(r1 * r1 * ss * (1.0f / 64.0f) + EPS);
; #pragma unroll
;                     for (int bj = 0; bj < 2; ++bj)
; #pragma unroll
;                         for (int n = 0; n < 2; ++n)
; #pragma unroll
;                             for (int e = 0; e < 4; ++e) v[bj][n][e] = acc[ai][bj][m][n][e] * sc * gn[bj][n][e];
;                     const float* rp = rope + (size_t)(row & (SEQ - 1)) * 16 + 4 * (fq & 1);
;                     const f32x4 cs = *(const f32x4*)rp, sn = *(const f32x4*)(rp + 8);
; #pragma unroll
;                     for (int e = 0; e < 4; ++e) {
;                         const float t1 = v[0][0][e], t2 = v[0][1][e];
;                         const float o1 = t1 * cs[e] - t2 * sn[e], o2 = t2 * cs[e] + t1 * sn[e];
;                         v[0][0][e] = fq < 2 ? o1 : t1; v[0][1][e] = fq < 2 ? o2 : t2;
;                     }
;                 } else {
; #pragma unroll
;                     for (int bj = 0; bj < 2; ++bj)
; #pragma unroll
;                         for (int n = 0; n < 2; ++n)
; #pragma unroll
;                             for (int e = 0; e < 4; ++e) { const float z = acc[ai][bj][m][n][e] * rstd[ai][m]; v[bj][n][e] = TYPE == 3 ? z * __builtin_amdgcn_rcpf(1.0f + __expf(-z)) : z; }
;                 }
;                 bf16_t* rowp = dst + (size_t)row * ld;
; #pragma unroll
;                 for (int bj = 0; bj < 2; ++bj) {
;                     u32x4 w; w.x = pkbf(v[bj][0][0], v[bj][0][1]); w.y = pkbf(v[bj][0][2], v[bj][0][3]); w.z = pkbf(v[bj][1][0], v[bj][1][1]); w.w = pkbf(v[bj][1][2], v[bj][1][3]);
;                     *(u32x4*)(rowp + 32 * bj) = w;
	v_mov_b32_e32 v25, v36
	v_pk_mul_f32 v[24:25], v[24:25], v[44:45]
	v_mov_b32_e32 v44, v23
	v_sub_f32_e32 v24, v24, v25
	v_cndmask_b32_e64 v41, v22, v24, s[38:39]
	v_mov_b32_e32 v24, v33
	v_mov_b32_e32 v25, v37
	v_mov_b32_e32 v45, v17
	v_pk_mul_f32 v[24:25], v[24:25], v[44:45]
	v_pk_mul_f32 v[18:19], v[18:19], v[40:41] op_sel_hi:[1,0]
	v_sub_f32_e32 v44, v24, v25
	v_pk_mul_f32 v[24:25], v[32:33], v[16:17]
	v_pk_mul_f32 v[18:19], v[132:133], v[18:19]
	v_pk_fma_f32 v[24:25], v[36:37], v[22:23], v[24:25]
	v_cndmask_b32_e64 v32, v23, v44, s[38:39]
	v_cndmask_b32_e64 v33, v17, v25, s[38:39]
	v_cndmask_b32_e64 v36, v16, v24, s[38:39]
	v_pk_mul_f32 v[16:17], v[26:27], v[40:41] op_sel_hi:[1,0]
	v_mov_b32_e32 v22, v34
	v_pk_mul_f32 v[16:17], v[130:131], v[16:17]
	v_mov_b32_e32 v23, v38
	v_mov_b32_e32 v24, v16
	v_mov_b32_e32 v25, v18
	v_pk_mul_f32 v[22:23], v[22:23], v[24:25]
	v_mov_b32_e32 v24, v17
	v_sub_f32_e32 v22, v22, v23
	v_cndmask_b32_e64 v26, v16, v22, s[38:39]
	v_mov_b32_e32 v22, v35
	v_mov_b32_e32 v23, v39
	v_mov_b32_e32 v25, v19
	v_pk_mul_f32 v[22:23], v[22:23], v[24:25]
	s_nop 0
	v_sub_f32_e32 v24, v22, v23
	v_pk_mul_f32 v[22:23], v[34:35], v[18:19]
	s_nop 0
	v_pk_fma_f32 v[22:23], v[38:39], v[16:17], v[22:23]
	v_cndmask_b32_e64 v17, v17, v24, s[38:39]
	v_cndmask_b32_e64 v19, v19, v23, s[38:39]
	v_cndmask_b32_e64 v22, v18, v22, s[38:39]
	v_cvt_pk_bf16_f32 v16, v41, v32
	v_cvt_pk_bf16_f32 v17, v26, v17
	v_cvt_pk_bf16_f32 v18, v36, v33
	v_cvt_pk_bf16_f32 v19, v22, v19
	global_store_dwordx4 v[42:43], v[16:19], off
	global_store_dwordx4 v[42:43], v[28:31], off offset:64
	global_load_dwordx4 v[16:19], v[20:21], off offset:32
	s_nop 0
	global_load_dwordx4 v[20:23], v[20:21], off
	v_mul_f32_e32 v24, v13, v13
	v_fmac_f32_e32 v24, v12, v12
	v_fmac_f32_e32 v24, v14, v14
	v_fmac_f32_e32 v24, v15, v15
	v_fmac_f32_e32 v24, v8, v8
	v_fmac_f32_e32 v24, v9, v9
	v_fmac_f32_e32 v24, v10, v10
	v_fmac_f32_e32 v24, v11, v11
	v_fmac_f32_e32 v24, v4, v4
	v_fmac_f32_e32 v24, v5, v5
	v_fmac_f32_e32 v24, v6, v6
	v_fmac_f32_e32 v24, v7, v7
	v_fmac_f32_e32 v24, v0, v0
	v_fmac_f32_e32 v24, v1, v1
	v_fmac_f32_e32 v24, v2, v2
	v_fmac_f32_e32 v24, v3, v3
	v_mov_b32_e32 v25, v24
	s_nop 1
	v_permlane16_swap_b32_e32 v24, v25
	v_add_f32_e32 v24, v24, v25
	v_mov_b32_e32 v25, v24
	s_nop 1
	v_permlane32_swap_b32_e32 v24, v25
	v_add_f32_e32 v24, v24, v25
	v_mul_f32_e32 v25, v172, v172
	v_mul_f32_e32 v24, v25, v24
	v_fmamk_f32 v24, v24, 0x3c800000, v198
	v_rsq_f32_e32 v24, v24
	s_nop 0
	v_mul_f32_e32 v24, v172, v24
	v_pk_mul_f32 v[0:1], v[0:1], v[24:25] op_sel_hi:[1,0]
	v_pk_mul_f32 v[4:5], v[4:5], v[24:25] op_sel_hi:[1,0]
	v_pk_mul_f32 v[144:145], v[124:125], v[0:1]
	v_pk_mul_f32 v[0:1], v[2:3], v[24:25] op_sel_hi:[1,0]
	v_pk_mul_f32 v[2:3], v[8:9], v[24:25] op_sel_hi:[1,0]
	v_pk_mul_f32 v[146:147], v[122:123], v[0:1]
	v_pk_mul_f32 v[0:1], v[12:13], v[24:25] op_sel_hi:[1,0]
	v_pk_mul_f32 v[2:3], v[114:115], v[2:3]
	v_pk_mul_f32 v[140:141], v[128:129], v[4:5]
	v_pk_mul_f32 v[4:5], v[6:7], v[24:25] op_sel_hi:[1,0]
	v_pk_mul_f32 v[0:1], v[118:119], v[0:1]
	v_pk_mul_f32 v[6:7], v[10:11], v[24:25] op_sel_hi:[1,0]
	v_pk_mul_f32 v[142:143], v[126:127], v[4:5]
	v_pk_mul_f32 v[4:5], v[14:15], v[24:25] op_sel_hi:[1,0]
	v_pk_mul_f32 v[6:7], v[132:133], v[6:7]
	v_pk_mul_f32 v[4:5], v[130:131], v[4:5]
	s_waitcnt vmcnt(1)
	v_pk_mul_f32 v[8:9], v[16:17], v[2:3]
	s_waitcnt vmcnt(0)
	v_pk_mul_f32 v[10:11], v[20:21], v[2:3]
	v_pk_fma_f32 v[8:9], v[20:21], v[0:1], v[8:9] neg_lo:[0,0,1] neg_hi:[0,0,1]
	v_pk_fma_f32 v[10:11], v[16:17], v[0:1], v[10:11]
	v_cndmask_b32_e64 v133, v1, v9, s[38:39]
	v_cndmask_b32_e64 v132, v0, v8, s[38:39]
	v_cndmask_b32_e64 v137, v3, v11, s[38:39]
	v_cndmask_b32_e64 v136, v2, v10, s[38:39]
	v_pk_mul_f32 v[0:1], v[18:19], v[6:7]
	v_pk_mul_f32 v[2:3], v[22:23], v[6:7]
	v_pk_fma_f32 v[0:1], v[22:23], v[4:5], v[0:1] neg_lo:[0,0,1] neg_hi:[0,0,1]
	v_pk_fma_f32 v[2:3], v[18:19], v[4:5], v[2:3]
	v_cndmask_b32_e64 v135, v5, v1, s[38:39]
	v_cndmask_b32_e64 v134, v4, v0, s[38:39]
	v_cndmask_b32_e64 v139, v7, v3, s[38:39]
	v_cndmask_b32_e64 v138, v6, v2, s[38:39]
.LBB0_337:
	v_ashrrev_i32_e32 v0, 31, v148
	s_nop 0
	s_nop 0
	v_mul_lo_u32 v0, s26, v148
	v_mov_b32_e64 v1, 0
	v_lshl_add_u64 v[4:5], v[0:1], 1, v[170:171]
	v_cvt_pk_bf16_f32 v0, v132, v133
	v_cvt_pk_bf16_f32 v1, v134, v135
	v_cvt_pk_bf16_f32 v2, v136, v137
	v_cvt_pk_bf16_f32 v3, v138, v139
	global_store_dwordx4 v[4:5], v[0:3], off
	s_andn2_b64 vcc, exec, s[40:41]
	s_mov_b64 s[26:27], -1
	v_cvt_pk_bf16_f32 v0, v140, v141
	v_cvt_pk_bf16_f32 v1, v142, v143
	v_cvt_pk_bf16_f32 v2, v144, v145
	v_cvt_pk_bf16_f32 v3, v146, v147
	global_store_dwordx4 v[4:5], v[0:3], off offset:64
	s_cbranch_vccnz .LBB0_296
	s_andn2_b64 vcc, exec, s[8:9]
	s_cbranch_vccnz .LBB0_295
	s_barrier
	s_branch .LBB0_295
